# cand E + the adjacent s_setprio 0 / s_setprio 1 pair between the two MFMA clusters of each mainloop phase removed (7 loops x 4)
# speedup vs baseline: 1.0021x; 1.0021x over previous
.LBB0_341:
	ds_read_b128 v[152:155], v139
	ds_read_b128 v[156:159], v139 offset:1024
	ds_read_b128 v[160:163], v139 offset:2048
	ds_read_b128 v[174:177], v139 offset:3072
	ds_read_b128 v[182:185], v168
	ds_read_b128 v[186:189], v168 offset:1024
	ds_read_b128 v[190:193], v168 offset:2048
	ds_read_b128 v[194:197], v168 offset:3072
	s_add_u32 s26, s24, 0xfffc0080
	s_addc_u32 s27, s25, -1
	s_cmp_eq_u32 s64, 12
	s_cselect_b32 s29, s1, s27
	s_cselect_b32 s28, s5, s26
	s_cselect_b32 s27, s17, s31
	s_cselect_b32 s26, s19, s30
	v_lshl_add_u64 v[164:165], s[24:25], 0, v[144:145]
	s_add_i32 m0, s47, 0xc000
	ds_read_b128 v[198:201], v169
	ds_read_b128 v[202:205], v169 offset:1024
	ds_read_b128 v[206:209], v169 offset:2048
	ds_read_b128 v[210:213], v169 offset:3072
	ds_read_b128 v[214:217], v169 offset:4096
	ds_read_b128 v[218:221], v169 offset:5120
	ds_read_b128 v[222:225], v169 offset:6144
	ds_read_b128 v[226:229], v169 offset:7168
	global_load_lds_dwordx4 v[164:165], off
	v_lshl_add_u64 v[164:165], s[24:25], 0, v[146:147]
	s_add_i32 m0, s47, 0xe000
	s_nop 0
	global_load_lds_dwordx4 v[164:165], off
	s_waitcnt vmcnt(8)
	s_waitcnt lgkmcnt(0)
	s_barrier
	s_setprio 1
	s_waitcnt lgkmcnt(0)
	v_mfma_f32_16x16x32_bf16 v[124:127], v[152:155], v[198:201], v[124:127]
	v_mfma_f32_16x16x32_bf16 v[120:123], v[160:163], v[198:201], v[120:123]
	v_mfma_f32_16x16x32_bf16 v[108:111], v[152:155], v[206:209], v[108:111]
	v_mfma_f32_16x16x32_bf16 v[104:107], v[160:163], v[206:209], v[104:107]
	v_mfma_f32_16x16x32_bf16 v[92:95], v[152:155], v[214:217], v[92:95]
	v_mfma_f32_16x16x32_bf16 v[88:91], v[160:163], v[214:217], v[88:91]
	v_mfma_f32_16x16x32_bf16 v[76:79], v[152:155], v[222:225], v[76:79]
	v_mfma_f32_16x16x32_bf16 v[72:75], v[160:163], v[222:225], v[72:75]
	v_mfma_f32_16x16x32_bf16 v[124:127], v[156:159], v[202:205], v[124:127]
	v_mfma_f32_16x16x32_bf16 v[120:123], v[174:177], v[202:205], v[120:123]
	v_mfma_f32_16x16x32_bf16 v[108:111], v[156:159], v[210:213], v[108:111]
	v_mfma_f32_16x16x32_bf16 v[104:107], v[174:177], v[210:213], v[104:107]
	v_mfma_f32_16x16x32_bf16 v[92:95], v[156:159], v[218:221], v[92:95]
	v_mfma_f32_16x16x32_bf16 v[88:91], v[174:177], v[218:221], v[88:91]
	v_mfma_f32_16x16x32_bf16 v[76:79], v[156:159], v[226:229], v[76:79]
	v_mfma_f32_16x16x32_bf16 v[72:75], v[174:177], v[226:229], v[72:75]
	v_mfma_f32_16x16x32_bf16 v[116:119], v[182:185], v[198:201], v[116:119]
	v_mfma_f32_16x16x32_bf16 v[112:115], v[190:193], v[198:201], v[112:115]
	v_mfma_f32_16x16x32_bf16 v[100:103], v[182:185], v[206:209], v[100:103]
	v_mfma_f32_16x16x32_bf16 v[96:99], v[190:193], v[206:209], v[96:99]
	v_mfma_f32_16x16x32_bf16 v[84:87], v[182:185], v[214:217], v[84:87]
	v_mfma_f32_16x16x32_bf16 v[80:83], v[190:193], v[214:217], v[80:83]
	v_mfma_f32_16x16x32_bf16 v[68:71], v[182:185], v[222:225], v[68:71]
	v_mfma_f32_16x16x32_bf16 v[64:67], v[190:193], v[222:225], v[64:67]
	v_mfma_f32_16x16x32_bf16 v[116:119], v[186:189], v[202:205], v[116:119]
	v_mfma_f32_16x16x32_bf16 v[112:115], v[194:197], v[202:205], v[112:115]
	v_mfma_f32_16x16x32_bf16 v[100:103], v[186:189], v[210:213], v[100:103]
	v_mfma_f32_16x16x32_bf16 v[96:99], v[194:197], v[210:213], v[96:99]
	v_mfma_f32_16x16x32_bf16 v[84:87], v[186:189], v[218:221], v[84:87]
	v_mfma_f32_16x16x32_bf16 v[80:83], v[194:197], v[218:221], v[80:83]
	v_mfma_f32_16x16x32_bf16 v[68:71], v[186:189], v[226:229], v[68:71]
	v_mfma_f32_16x16x32_bf16 v[64:67], v[194:197], v[226:229], v[64:67]
	s_setprio 0
	s_barrier
	s_mov_b32 m0, s43
	v_lshl_add_u64 v[164:165], s[26:27], 0, v[130:131]
	s_add_u32 s66, s26, 0x40000
	ds_read_b128 v[198:201], v169 offset:16384
	ds_read_b128 v[202:205], v169 offset:17408
	ds_read_b128 v[206:209], v169 offset:18432
	ds_read_b128 v[210:213], v169 offset:19456
	ds_read_b128 v[214:217], v169 offset:20480
	ds_read_b128 v[218:221], v169 offset:21504
	ds_read_b128 v[222:225], v169 offset:22528
	ds_read_b128 v[226:229], v169 offset:23552
	global_load_lds_dwordx4 v[164:165], off
	v_lshl_add_u64 v[178:179], s[26:27], 0, v[134:135]
	s_mov_b32 m0, s44
	s_addc_u32 s67, s27, 0
	global_load_lds_dwordx4 v[178:179], off
	v_lshl_add_u64 v[230:231], s[66:67], 0, v[130:131]
	s_mov_b32 m0, s45
	v_lshl_add_u64 v[232:233], s[28:29], 0, v[132:133]
	global_load_lds_dwordx4 v[230:231], off
	v_lshl_add_u64 v[230:231], s[66:67], 0, v[134:135]
	s_mov_b32 m0, s46
	s_nop 0
	global_load_lds_dwordx4 v[230:231], off
	v_lshl_add_u64 v[230:231], s[28:29], 0, v[128:129]
	s_mov_b32 m0, s47
	s_nop 0
	global_load_lds_dwordx4 v[230:231], off
	s_mov_b32 m0, s48
	s_nop 0
	global_load_lds_dwordx4 v[232:233], off
	s_waitcnt vmcnt(8)
	s_waitcnt lgkmcnt(0)
	s_barrier
	s_setprio 1
	s_waitcnt lgkmcnt(0)
	v_mfma_f32_16x16x32_bf16 v[60:63], v[152:155], v[198:201], v[60:63]
	v_mfma_f32_16x16x32_bf16 v[56:59], v[160:163], v[198:201], v[56:59]
	v_mfma_f32_16x16x32_bf16 v[44:47], v[152:155], v[206:209], v[44:47]
	v_mfma_f32_16x16x32_bf16 v[40:43], v[160:163], v[206:209], v[40:43]
	v_mfma_f32_16x16x32_bf16 v[28:31], v[152:155], v[214:217], v[28:31]
	v_mfma_f32_16x16x32_bf16 v[24:27], v[160:163], v[214:217], v[24:27]
	v_mfma_f32_16x16x32_bf16 v[12:15], v[152:155], v[222:225], v[12:15]
	v_mfma_f32_16x16x32_bf16 v[8:11], v[160:163], v[222:225], v[8:11]
	v_mfma_f32_16x16x32_bf16 v[60:63], v[156:159], v[202:205], v[60:63]
	v_mfma_f32_16x16x32_bf16 v[56:59], v[174:177], v[202:205], v[56:59]
	v_mfma_f32_16x16x32_bf16 v[44:47], v[156:159], v[210:213], v[44:47]
	v_mfma_f32_16x16x32_bf16 v[40:43], v[174:177], v[210:213], v[40:43]
	v_mfma_f32_16x16x32_bf16 v[28:31], v[156:159], v[218:221], v[28:31]
	v_mfma_f32_16x16x32_bf16 v[24:27], v[174:177], v[218:221], v[24:27]
	v_mfma_f32_16x16x32_bf16 v[12:15], v[156:159], v[226:229], v[12:15]
	v_mfma_f32_16x16x32_bf16 v[8:11], v[174:177], v[226:229], v[8:11]
	v_mfma_f32_16x16x32_bf16 v[52:55], v[182:185], v[198:201], v[52:55]
	v_mfma_f32_16x16x32_bf16 v[48:51], v[190:193], v[198:201], v[48:51]
	v_mfma_f32_16x16x32_bf16 v[36:39], v[182:185], v[206:209], v[36:39]
	v_mfma_f32_16x16x32_bf16 v[32:35], v[190:193], v[206:209], v[32:35]
	v_mfma_f32_16x16x32_bf16 v[20:23], v[182:185], v[214:217], v[20:23]
	v_mfma_f32_16x16x32_bf16 v[16:19], v[190:193], v[214:217], v[16:19]
	v_mfma_f32_16x16x32_bf16 v[4:7], v[182:185], v[222:225], v[4:7]
	v_mfma_f32_16x16x32_bf16 v[0:3], v[190:193], v[222:225], v[0:3]
	v_mfma_f32_16x16x32_bf16 v[52:55], v[186:189], v[202:205], v[52:55]
	v_mfma_f32_16x16x32_bf16 v[48:51], v[194:197], v[202:205], v[48:51]
	v_mfma_f32_16x16x32_bf16 v[36:39], v[186:189], v[210:213], v[36:39]
	v_mfma_f32_16x16x32_bf16 v[32:35], v[194:197], v[210:213], v[32:35]
	v_mfma_f32_16x16x32_bf16 v[20:23], v[186:189], v[218:221], v[20:23]
	v_mfma_f32_16x16x32_bf16 v[16:19], v[194:197], v[218:221], v[16:19]
	v_mfma_f32_16x16x32_bf16 v[4:7], v[186:189], v[226:229], v[4:7]
	v_mfma_f32_16x16x32_bf16 v[0:3], v[194:197], v[226:229], v[0:3]
	s_setprio 0
	s_barrier
	ds_read_b128 v[152:155], v170
	ds_read_b128 v[156:159], v170 offset:1024
	ds_read_b128 v[160:163], v170 offset:2048
	ds_read_b128 v[174:177], v170 offset:3072
	ds_read_b128 v[182:185], v171
	ds_read_b128 v[186:189], v171 offset:1024
	ds_read_b128 v[190:193], v171 offset:2048
	ds_read_b128 v[194:197], v171 offset:3072
	s_add_u32 s28, s28, 0x40000
	s_addc_u32 s29, s29, 0
	s_mov_b32 m0, s49
	v_lshl_add_u64 v[234:235], s[28:29], 0, v[128:129]
	ds_read_b128 v[198:201], v169 offset:32768
	ds_read_b128 v[202:205], v169 offset:33792
	ds_read_b128 v[206:209], v169 offset:34816
	ds_read_b128 v[210:213], v169 offset:35840
	ds_read_b128 v[214:217], v169 offset:36864
	ds_read_b128 v[218:221], v169 offset:37888
	ds_read_b128 v[222:225], v169 offset:38912
	ds_read_b128 v[226:229], v169 offset:39936
	global_load_lds_dwordx4 v[234:235], off
	v_lshl_add_u64 v[234:235], s[28:29], 0, v[132:133]
	s_mov_b32 m0, s50
	s_nop 0
	global_load_lds_dwordx4 v[234:235], off
	s_waitcnt vmcnt(8)
	s_waitcnt lgkmcnt(0)
	s_barrier
	s_setprio 1
	s_waitcnt lgkmcnt(0)
	v_mfma_f32_16x16x32_bf16 v[124:127], v[152:155], v[198:201], v[124:127]
	v_mfma_f32_16x16x32_bf16 v[120:123], v[160:163], v[198:201], v[120:123]
	v_mfma_f32_16x16x32_bf16 v[108:111], v[152:155], v[206:209], v[108:111]
	v_mfma_f32_16x16x32_bf16 v[104:107], v[160:163], v[206:209], v[104:107]
	v_mfma_f32_16x16x32_bf16 v[92:95], v[152:155], v[214:217], v[92:95]
	v_mfma_f32_16x16x32_bf16 v[88:91], v[160:163], v[214:217], v[88:91]
	v_mfma_f32_16x16x32_bf16 v[76:79], v[152:155], v[222:225], v[76:79]
	v_mfma_f32_16x16x32_bf16 v[72:75], v[160:163], v[222:225], v[72:75]
	v_mfma_f32_16x16x32_bf16 v[124:127], v[156:159], v[202:205], v[124:127]
	v_mfma_f32_16x16x32_bf16 v[120:123], v[174:177], v[202:205], v[120:123]
	v_mfma_f32_16x16x32_bf16 v[108:111], v[156:159], v[210:213], v[108:111]
	v_mfma_f32_16x16x32_bf16 v[104:107], v[174:177], v[210:213], v[104:107]
	v_mfma_f32_16x16x32_bf16 v[92:95], v[156:159], v[218:221], v[92:95]
	v_mfma_f32_16x16x32_bf16 v[88:91], v[174:177], v[218:221], v[88:91]
	v_mfma_f32_16x16x32_bf16 v[76:79], v[156:159], v[226:229], v[76:79]
	v_mfma_f32_16x16x32_bf16 v[72:75], v[174:177], v[226:229], v[72:75]
	v_mfma_f32_16x16x32_bf16 v[116:119], v[182:185], v[198:201], v[116:119]
	v_mfma_f32_16x16x32_bf16 v[112:115], v[190:193], v[198:201], v[112:115]
	v_mfma_f32_16x16x32_bf16 v[100:103], v[182:185], v[206:209], v[100:103]
	v_mfma_f32_16x16x32_bf16 v[96:99], v[190:193], v[206:209], v[96:99]
	v_mfma_f32_16x16x32_bf16 v[84:87], v[182:185], v[214:217], v[84:87]
	v_mfma_f32_16x16x32_bf16 v[80:83], v[190:193], v[214:217], v[80:83]
	v_mfma_f32_16x16x32_bf16 v[68:71], v[182:185], v[222:225], v[68:71]
	v_mfma_f32_16x16x32_bf16 v[64:67], v[190:193], v[222:225], v[64:67]
	v_mfma_f32_16x16x32_bf16 v[116:119], v[186:189], v[202:205], v[116:119]
	v_mfma_f32_16x16x32_bf16 v[112:115], v[194:197], v[202:205], v[112:115]
	v_mfma_f32_16x16x32_bf16 v[100:103], v[186:189], v[210:213], v[100:103]
	v_mfma_f32_16x16x32_bf16 v[96:99], v[194:197], v[210:213], v[96:99]
	v_mfma_f32_16x16x32_bf16 v[84:87], v[186:189], v[218:221], v[84:87]
	v_mfma_f32_16x16x32_bf16 v[80:83], v[194:197], v[218:221], v[80:83]
	v_mfma_f32_16x16x32_bf16 v[68:71], v[186:189], v[226:229], v[68:71]
	v_mfma_f32_16x16x32_bf16 v[64:67], v[194:197], v[226:229], v[64:67]
	s_setprio 0
	s_barrier
	s_mov_b32 m0, s54
	v_lshl_add_u64 v[164:165], v[164:165], 0, s[12:13]
	s_add_u32 s26, s26, 0x40080
	ds_read_b128 v[198:201], v169 offset:49152
	ds_read_b128 v[202:205], v169 offset:50176
	ds_read_b128 v[206:209], v169 offset:51200
	ds_read_b128 v[210:213], v169 offset:52224
	ds_read_b128 v[214:217], v169 offset:53248
	ds_read_b128 v[218:221], v169 offset:54272
	ds_read_b128 v[222:225], v169 offset:55296
	ds_read_b128 v[226:229], v169 offset:56320
	global_load_lds_dwordx4 v[164:165], off
	v_lshl_add_u64 v[164:165], v[178:179], 0, s[12:13]
	s_mov_b32 m0, s55
	s_addc_u32 s27, s27, 0
	global_load_lds_dwordx4 v[164:165], off
	v_lshl_add_u64 v[164:165], s[26:27], 0, v[130:131]
	s_mov_b32 m0, s58
	s_nop 0
	global_load_lds_dwordx4 v[164:165], off
	v_lshl_add_u64 v[164:165], s[26:27], 0, v[134:135]
	s_mov_b32 m0, s59
	s_nop 0
	global_load_lds_dwordx4 v[164:165], off
	v_lshl_add_u64 v[164:165], v[230:231], 0, s[12:13]
	s_mov_b32 m0, s56
	s_nop 0
	global_load_lds_dwordx4 v[164:165], off
	v_lshl_add_u64 v[164:165], v[232:233], 0, s[12:13]
	s_mov_b32 m0, s57
	s_nop 0
	global_load_lds_dwordx4 v[164:165], off
	s_waitcnt vmcnt(8)
	s_waitcnt lgkmcnt(0)
	s_barrier
	s_setprio 1
	s_waitcnt lgkmcnt(0)
	v_mfma_f32_16x16x32_bf16 v[60:63], v[152:155], v[198:201], v[60:63]
	v_mfma_f32_16x16x32_bf16 v[56:59], v[160:163], v[198:201], v[56:59]
	v_mfma_f32_16x16x32_bf16 v[44:47], v[152:155], v[206:209], v[44:47]
	v_mfma_f32_16x16x32_bf16 v[40:43], v[160:163], v[206:209], v[40:43]
	v_mfma_f32_16x16x32_bf16 v[28:31], v[152:155], v[214:217], v[28:31]
	v_mfma_f32_16x16x32_bf16 v[24:27], v[160:163], v[214:217], v[24:27]
	v_mfma_f32_16x16x32_bf16 v[12:15], v[152:155], v[222:225], v[12:15]
	v_mfma_f32_16x16x32_bf16 v[8:11], v[160:163], v[222:225], v[8:11]
	v_mfma_f32_16x16x32_bf16 v[60:63], v[156:159], v[202:205], v[60:63]
	v_mfma_f32_16x16x32_bf16 v[56:59], v[174:177], v[202:205], v[56:59]
	v_mfma_f32_16x16x32_bf16 v[44:47], v[156:159], v[210:213], v[44:47]
	v_mfma_f32_16x16x32_bf16 v[40:43], v[174:177], v[210:213], v[40:43]
	v_mfma_f32_16x16x32_bf16 v[28:31], v[156:159], v[218:221], v[28:31]
	v_mfma_f32_16x16x32_bf16 v[24:27], v[174:177], v[218:221], v[24:27]
	v_mfma_f32_16x16x32_bf16 v[12:15], v[156:159], v[226:229], v[12:15]
	v_mfma_f32_16x16x32_bf16 v[8:11], v[174:177], v[226:229], v[8:11]
	v_mfma_f32_16x16x32_bf16 v[52:55], v[182:185], v[198:201], v[52:55]
	v_mfma_f32_16x16x32_bf16 v[48:51], v[190:193], v[198:201], v[48:51]
	v_mfma_f32_16x16x32_bf16 v[36:39], v[182:185], v[206:209], v[36:39]
	v_mfma_f32_16x16x32_bf16 v[32:35], v[190:193], v[206:209], v[32:35]
	v_mfma_f32_16x16x32_bf16 v[20:23], v[182:185], v[214:217], v[20:23]
	v_mfma_f32_16x16x32_bf16 v[16:19], v[190:193], v[214:217], v[16:19]
	v_mfma_f32_16x16x32_bf16 v[4:7], v[182:185], v[222:225], v[4:7]
	v_mfma_f32_16x16x32_bf16 v[0:3], v[190:193], v[222:225], v[0:3]
	v_mfma_f32_16x16x32_bf16 v[52:55], v[186:189], v[202:205], v[52:55]
	v_mfma_f32_16x16x32_bf16 v[48:51], v[194:197], v[202:205], v[48:51]
	v_mfma_f32_16x16x32_bf16 v[36:39], v[186:189], v[210:213], v[36:39]
	v_mfma_f32_16x16x32_bf16 v[32:35], v[194:197], v[210:213], v[32:35]
	v_mfma_f32_16x16x32_bf16 v[20:23], v[186:189], v[218:221], v[20:23]
	v_mfma_f32_16x16x32_bf16 v[16:19], v[194:197], v[218:221], v[16:19]
	v_mfma_f32_16x16x32_bf16 v[4:7], v[186:189], v[226:229], v[4:7]
	v_mfma_f32_16x16x32_bf16 v[0:3], v[194:197], v[226:229], v[0:3]
	s_setprio 0
	s_barrier
	s_add_i32 s64, s64, 2
	s_add_u32 s24, s24, 0x100
	s_addc_u32 s25, s25, 0
	s_add_u32 s30, s30, 0x100
	s_addc_u32 s31, s31, 0
	s_cmp_gt_u32 s64, 13
	s_cbranch_scc0 .LBB0_341
	s_and_b64 vcc, exec, s[14:15]
	s_cbranch_vccz .LBB0_344
	s_barrier

.LBB0_596:
	v_add_u32_e32 v178, s95, v165
	v_add_u32_e32 v200, s86, v165
	ds_read_b128 v[156:159], v178
	ds_read_b128 v[170:173], v178 offset:1024
	ds_read_b128 v[174:177], v178 offset:2048
	ds_read_b128 v[178:181], v178 offset:3072
	ds_read_b128 v[182:185], v200
	ds_read_b128 v[186:189], v200 offset:1024
	ds_read_b128 v[190:193], v200 offset:2048
	ds_read_b128 v[204:207], v200 offset:3072
	s_add_u32 s43, s44, 0xfffc0080
	s_addc_u32 s72, s45, -1
	s_cmp_eq_u32 s42, 12
	s_cselect_b32 s77, s57, s72
	s_cselect_b32 s76, s91, s43
	s_cselect_b32 vcc_hi, s1, s65
	s_cselect_b32 vcc_lo, s53, s64
	v_lshl_add_u64 v[232:233], s[44:45], 0, v[152:153]
	s_add_i32 m0, s48, 0xc000
	ds_read_b128 v[208:211], v169
	ds_read_b128 v[212:215], v169 offset:1024
	ds_read_b128 v[216:219], v169 offset:2048
	ds_read_b128 v[220:223], v169 offset:3072
	ds_read_b128 v[224:227], v169 offset:4096
	ds_read_b128 v[228:231], v169 offset:5120
	ds_read_b128 v[238:241], v169 offset:6144
	ds_read_b128 v[242:245], v169 offset:7168
	global_load_lds_dwordx4 v[232:233], off
	v_lshl_add_u64 v[232:233], s[44:45], 0, v[154:155]
	s_add_i32 m0, s48, 0xe000
	s_nop 0
	global_load_lds_dwordx4 v[232:233], off
	s_waitcnt vmcnt(8)
	s_waitcnt lgkmcnt(0)
	s_barrier
	s_setprio 1
	s_waitcnt lgkmcnt(0)
	v_mfma_f32_16x16x32_bf16 v[142:145], v[156:159], v[208:211], v[142:145]
	v_mfma_f32_16x16x32_bf16 v[138:141], v[174:177], v[208:211], v[138:141]
	v_mfma_f32_16x16x32_bf16 v[126:129], v[156:159], v[216:219], v[126:129]
	v_mfma_f32_16x16x32_bf16 v[122:125], v[174:177], v[216:219], v[122:125]
	v_mfma_f32_16x16x32_bf16 v[110:113], v[156:159], v[224:227], v[110:113]
	v_mfma_f32_16x16x32_bf16 v[106:109], v[174:177], v[224:227], v[106:109]
	v_mfma_f32_16x16x32_bf16 v[94:97], v[156:159], v[238:241], v[94:97]
	v_mfma_f32_16x16x32_bf16 v[90:93], v[174:177], v[238:241], v[90:93]
	v_mfma_f32_16x16x32_bf16 v[142:145], v[170:173], v[212:215], v[142:145]
	v_mfma_f32_16x16x32_bf16 v[138:141], v[178:181], v[212:215], v[138:141]
	v_mfma_f32_16x16x32_bf16 v[126:129], v[170:173], v[220:223], v[126:129]
	v_mfma_f32_16x16x32_bf16 v[122:125], v[178:181], v[220:223], v[122:125]
	v_mfma_f32_16x16x32_bf16 v[110:113], v[170:173], v[228:231], v[110:113]
	v_mfma_f32_16x16x32_bf16 v[106:109], v[178:181], v[228:231], v[106:109]
	v_mfma_f32_16x16x32_bf16 v[94:97], v[170:173], v[242:245], v[94:97]
	v_mfma_f32_16x16x32_bf16 v[90:93], v[178:181], v[242:245], v[90:93]
	v_mfma_f32_16x16x32_bf16 v[134:137], v[182:185], v[208:211], v[134:137]
	v_mfma_f32_16x16x32_bf16 v[130:133], v[190:193], v[208:211], v[130:133]
	v_mfma_f32_16x16x32_bf16 v[118:121], v[182:185], v[216:219], v[118:121]
	v_mfma_f32_16x16x32_bf16 v[114:117], v[190:193], v[216:219], v[114:117]
	v_mfma_f32_16x16x32_bf16 v[102:105], v[182:185], v[224:227], v[102:105]
	v_mfma_f32_16x16x32_bf16 v[98:101], v[190:193], v[224:227], v[98:101]
	v_mfma_f32_16x16x32_bf16 v[86:89], v[182:185], v[238:241], v[86:89]
	v_mfma_f32_16x16x32_bf16 v[82:85], v[190:193], v[238:241], v[82:85]
	v_mfma_f32_16x16x32_bf16 v[134:137], v[186:189], v[212:215], v[134:137]
	v_mfma_f32_16x16x32_bf16 v[130:133], v[204:207], v[212:215], v[130:133]
	v_mfma_f32_16x16x32_bf16 v[118:121], v[186:189], v[220:223], v[118:121]
	v_mfma_f32_16x16x32_bf16 v[114:117], v[204:207], v[220:223], v[114:117]
	v_mfma_f32_16x16x32_bf16 v[102:105], v[186:189], v[228:231], v[102:105]
	v_mfma_f32_16x16x32_bf16 v[98:101], v[204:207], v[228:231], v[98:101]
	v_mfma_f32_16x16x32_bf16 v[86:89], v[186:189], v[242:245], v[86:89]
	v_mfma_f32_16x16x32_bf16 v[82:85], v[204:207], v[242:245], v[82:85]
	s_setprio 0
	s_barrier
	s_mov_b32 m0, s55
	v_lshl_add_u64 v[232:233], vcc, 0, v[0:1]
	s_add_u32 s72, vcc_lo, 0x40000
	ds_read_b128 v[208:211], v169 offset:16384
	ds_read_b128 v[212:215], v169 offset:17408
	ds_read_b128 v[216:219], v169 offset:18432
	ds_read_b128 v[220:223], v169 offset:19456
	ds_read_b128 v[224:227], v169 offset:20480
	ds_read_b128 v[228:231], v169 offset:21504
	ds_read_b128 v[238:241], v169 offset:22528
	ds_read_b128 v[242:245], v169 offset:23552
	global_load_lds_dwordx4 v[232:233], off
	v_lshl_add_u64 v[246:247], vcc, 0, v[150:151]
	s_mov_b32 m0, s85
	s_addc_u32 s73, vcc_hi, 0
	global_load_lds_dwordx4 v[246:247], off
	v_lshl_add_u64 v[248:249], s[72:73], 0, v[0:1]
	s_mov_b32 m0, s58
	v_lshl_add_u64 v[250:251], s[76:77], 0, v[148:149]
	global_load_lds_dwordx4 v[248:249], off
	v_lshl_add_u64 v[248:249], s[72:73], 0, v[150:151]
	s_mov_b32 m0, s97
	s_nop 0
	global_load_lds_dwordx4 v[248:249], off
	v_lshl_add_u64 v[248:249], s[76:77], 0, v[146:147]
	s_mov_b32 m0, s48
	s_nop 0
	global_load_lds_dwordx4 v[248:249], off
	s_mov_b32 m0, s59
	s_nop 0
	global_load_lds_dwordx4 v[250:251], off
	s_waitcnt vmcnt(8)
	s_waitcnt lgkmcnt(0)
	s_barrier
	s_setprio 1
	s_waitcnt lgkmcnt(0)
	v_mfma_f32_16x16x32_bf16 v[78:81], v[156:159], v[208:211], v[78:81]
	v_mfma_f32_16x16x32_bf16 v[74:77], v[174:177], v[208:211], v[74:77]
	v_mfma_f32_16x16x32_bf16 v[66:69], v[156:159], v[216:219], v[66:69]
	v_mfma_f32_16x16x32_bf16 v[58:61], v[174:177], v[216:219], v[58:61]
	v_mfma_f32_16x16x32_bf16 v[46:49], v[156:159], v[224:227], v[46:49]
	v_mfma_f32_16x16x32_bf16 v[42:45], v[174:177], v[224:227], v[42:45]
	v_mfma_f32_16x16x32_bf16 v[30:33], v[156:159], v[238:241], v[30:33]
	v_mfma_f32_16x16x32_bf16 v[26:29], v[174:177], v[238:241], v[26:29]
	v_mfma_f32_16x16x32_bf16 v[78:81], v[170:173], v[212:215], v[78:81]
	v_mfma_f32_16x16x32_bf16 v[74:77], v[178:181], v[212:215], v[74:77]
	v_mfma_f32_16x16x32_bf16 v[66:69], v[170:173], v[220:223], v[66:69]
	v_mfma_f32_16x16x32_bf16 v[58:61], v[178:181], v[220:223], v[58:61]
	v_mfma_f32_16x16x32_bf16 v[46:49], v[170:173], v[228:231], v[46:49]
	v_mfma_f32_16x16x32_bf16 v[42:45], v[178:181], v[228:231], v[42:45]
	v_mfma_f32_16x16x32_bf16 v[30:33], v[170:173], v[242:245], v[30:33]
	v_mfma_f32_16x16x32_bf16 v[26:29], v[178:181], v[242:245], v[26:29]
	v_mfma_f32_16x16x32_bf16 v[70:73], v[182:185], v[208:211], v[70:73]
	v_mfma_f32_16x16x32_bf16 v[62:65], v[190:193], v[208:211], v[62:65]
	v_mfma_f32_16x16x32_bf16 v[54:57], v[182:185], v[216:219], v[54:57]
	v_mfma_f32_16x16x32_bf16 v[50:53], v[190:193], v[216:219], v[50:53]
	v_mfma_f32_16x16x32_bf16 v[38:41], v[182:185], v[224:227], v[38:41]
	v_mfma_f32_16x16x32_bf16 v[34:37], v[190:193], v[224:227], v[34:37]
	v_mfma_f32_16x16x32_bf16 v[22:25], v[182:185], v[238:241], v[22:25]
	v_mfma_f32_16x16x32_bf16 v[18:21], v[190:193], v[238:241], v[18:21]
	v_mfma_f32_16x16x32_bf16 v[70:73], v[186:189], v[212:215], v[70:73]
	v_mfma_f32_16x16x32_bf16 v[62:65], v[204:207], v[212:215], v[62:65]
	v_mfma_f32_16x16x32_bf16 v[54:57], v[186:189], v[220:223], v[54:57]
	v_mfma_f32_16x16x32_bf16 v[50:53], v[204:207], v[220:223], v[50:53]
	v_mfma_f32_16x16x32_bf16 v[38:41], v[186:189], v[228:231], v[38:41]
	v_mfma_f32_16x16x32_bf16 v[34:37], v[204:207], v[228:231], v[34:37]
	v_mfma_f32_16x16x32_bf16 v[22:25], v[186:189], v[242:245], v[22:25]
	v_mfma_f32_16x16x32_bf16 v[18:21], v[204:207], v[242:245], v[18:21]
	s_setprio 0
	s_barrier
	v_add_u32_e32 v178, s87, v165
	v_add_u32_e32 v200, s92, v165
	ds_read_b128 v[156:159], v178
	ds_read_b128 v[170:173], v178 offset:1024
	ds_read_b128 v[174:177], v178 offset:2048
	ds_read_b128 v[178:181], v178 offset:3072
	ds_read_b128 v[182:185], v200
	ds_read_b128 v[186:189], v200 offset:1024
	ds_read_b128 v[190:193], v200 offset:2048
	ds_read_b128 v[204:207], v200 offset:3072
	s_add_u32 s72, s76, 0x40000
	s_addc_u32 s73, s77, 0
	s_mov_b32 m0, s82
	v_lshl_add_u64 v[200:201], s[72:73], 0, v[146:147]
	ds_read_b128 v[208:211], v169 offset:32768
	ds_read_b128 v[212:215], v169 offset:33792
	ds_read_b128 v[216:219], v169 offset:34816
	ds_read_b128 v[220:223], v169 offset:35840
	ds_read_b128 v[224:227], v169 offset:36864
	ds_read_b128 v[228:231], v169 offset:37888
	ds_read_b128 v[238:241], v169 offset:38912
	ds_read_b128 v[242:245], v169 offset:39936
	global_load_lds_dwordx4 v[200:201], off
	v_lshl_add_u64 v[200:201], s[72:73], 0, v[148:149]
	s_mov_b32 m0, s50
	s_nop 0
	global_load_lds_dwordx4 v[200:201], off
	s_waitcnt vmcnt(8)
	s_waitcnt lgkmcnt(0)
	s_barrier
	s_setprio 1
	s_waitcnt lgkmcnt(0)
	v_mfma_f32_16x16x32_bf16 v[142:145], v[156:159], v[208:211], v[142:145]
	v_mfma_f32_16x16x32_bf16 v[138:141], v[174:177], v[208:211], v[138:141]
	v_mfma_f32_16x16x32_bf16 v[126:129], v[156:159], v[216:219], v[126:129]
	v_mfma_f32_16x16x32_bf16 v[122:125], v[174:177], v[216:219], v[122:125]
	v_mfma_f32_16x16x32_bf16 v[110:113], v[156:159], v[224:227], v[110:113]
	v_mfma_f32_16x16x32_bf16 v[106:109], v[174:177], v[224:227], v[106:109]
	v_mfma_f32_16x16x32_bf16 v[94:97], v[156:159], v[238:241], v[94:97]
	v_mfma_f32_16x16x32_bf16 v[90:93], v[174:177], v[238:241], v[90:93]
	v_mfma_f32_16x16x32_bf16 v[142:145], v[170:173], v[212:215], v[142:145]
	v_mfma_f32_16x16x32_bf16 v[138:141], v[178:181], v[212:215], v[138:141]
	v_mfma_f32_16x16x32_bf16 v[126:129], v[170:173], v[220:223], v[126:129]
	v_mfma_f32_16x16x32_bf16 v[122:125], v[178:181], v[220:223], v[122:125]
	v_mfma_f32_16x16x32_bf16 v[110:113], v[170:173], v[228:231], v[110:113]
	v_mfma_f32_16x16x32_bf16 v[106:109], v[178:181], v[228:231], v[106:109]
	v_mfma_f32_16x16x32_bf16 v[94:97], v[170:173], v[242:245], v[94:97]
	v_mfma_f32_16x16x32_bf16 v[90:93], v[178:181], v[242:245], v[90:93]
	v_mfma_f32_16x16x32_bf16 v[134:137], v[182:185], v[208:211], v[134:137]
	v_mfma_f32_16x16x32_bf16 v[130:133], v[190:193], v[208:211], v[130:133]
	v_mfma_f32_16x16x32_bf16 v[118:121], v[182:185], v[216:219], v[118:121]
	v_mfma_f32_16x16x32_bf16 v[114:117], v[190:193], v[216:219], v[114:117]
	v_mfma_f32_16x16x32_bf16 v[102:105], v[182:185], v[224:227], v[102:105]
	v_mfma_f32_16x16x32_bf16 v[98:101], v[190:193], v[224:227], v[98:101]
	v_mfma_f32_16x16x32_bf16 v[86:89], v[182:185], v[238:241], v[86:89]
	v_mfma_f32_16x16x32_bf16 v[82:85], v[190:193], v[238:241], v[82:85]
	v_mfma_f32_16x16x32_bf16 v[134:137], v[186:189], v[212:215], v[134:137]
	v_mfma_f32_16x16x32_bf16 v[130:133], v[204:207], v[212:215], v[130:133]
	v_mfma_f32_16x16x32_bf16 v[118:121], v[186:189], v[220:223], v[118:121]
	v_mfma_f32_16x16x32_bf16 v[114:117], v[204:207], v[220:223], v[114:117]
	v_mfma_f32_16x16x32_bf16 v[102:105], v[186:189], v[228:231], v[102:105]
	v_mfma_f32_16x16x32_bf16 v[98:101], v[204:207], v[228:231], v[98:101]
	v_mfma_f32_16x16x32_bf16 v[86:89], v[186:189], v[242:245], v[86:89]
	v_mfma_f32_16x16x32_bf16 v[82:85], v[204:207], v[242:245], v[82:85]
	s_setprio 0
	s_barrier
	s_mov_b32 m0, s60
	v_lshl_add_u64 v[200:201], v[232:233], 0, s[80:81]
	s_add_u32 s72, vcc_lo, 0x40080
	ds_read_b128 v[208:211], v169 offset:49152
	ds_read_b128 v[212:215], v169 offset:50176
	ds_read_b128 v[216:219], v169 offset:51200
	ds_read_b128 v[220:223], v169 offset:52224
	ds_read_b128 v[224:227], v169 offset:53248
	ds_read_b128 v[228:231], v169 offset:54272
	ds_read_b128 v[238:241], v169 offset:55296
	ds_read_b128 v[242:245], v169 offset:56320
	global_load_lds_dwordx4 v[200:201], off
	v_lshl_add_u64 v[200:201], v[246:247], 0, s[80:81]
	s_mov_b32 m0, s61
	s_addc_u32 s73, vcc_hi, 0
	global_load_lds_dwordx4 v[200:201], off
	v_lshl_add_u64 v[200:201], s[72:73], 0, v[0:1]
	s_mov_b32 m0, s66
	s_nop 0
	global_load_lds_dwordx4 v[200:201], off
	v_lshl_add_u64 v[200:201], s[72:73], 0, v[150:151]
	s_mov_b32 m0, s83
	s_nop 0
	global_load_lds_dwordx4 v[200:201], off
	v_lshl_add_u64 v[200:201], v[248:249], 0, s[80:81]
	s_mov_b32 m0, s62
	s_nop 0
	global_load_lds_dwordx4 v[200:201], off
	v_lshl_add_u64 v[200:201], v[250:251], 0, s[80:81]
	s_mov_b32 m0, s63
	s_nop 0
	global_load_lds_dwordx4 v[200:201], off
	s_waitcnt vmcnt(8)
	s_waitcnt lgkmcnt(0)
	s_barrier
	s_setprio 1
	s_waitcnt lgkmcnt(0)
	v_mfma_f32_16x16x32_bf16 v[78:81], v[156:159], v[208:211], v[78:81]
	v_mfma_f32_16x16x32_bf16 v[74:77], v[174:177], v[208:211], v[74:77]
	v_mfma_f32_16x16x32_bf16 v[66:69], v[156:159], v[216:219], v[66:69]
	v_mfma_f32_16x16x32_bf16 v[58:61], v[174:177], v[216:219], v[58:61]
	v_mfma_f32_16x16x32_bf16 v[46:49], v[156:159], v[224:227], v[46:49]
	v_mfma_f32_16x16x32_bf16 v[42:45], v[174:177], v[224:227], v[42:45]
	v_mfma_f32_16x16x32_bf16 v[30:33], v[156:159], v[238:241], v[30:33]
	v_mfma_f32_16x16x32_bf16 v[26:29], v[174:177], v[238:241], v[26:29]
	v_mfma_f32_16x16x32_bf16 v[78:81], v[170:173], v[212:215], v[78:81]
	v_mfma_f32_16x16x32_bf16 v[74:77], v[178:181], v[212:215], v[74:77]
	v_mfma_f32_16x16x32_bf16 v[66:69], v[170:173], v[220:223], v[66:69]
	v_mfma_f32_16x16x32_bf16 v[58:61], v[178:181], v[220:223], v[58:61]
	v_mfma_f32_16x16x32_bf16 v[46:49], v[170:173], v[228:231], v[46:49]
	v_mfma_f32_16x16x32_bf16 v[42:45], v[178:181], v[228:231], v[42:45]
	v_mfma_f32_16x16x32_bf16 v[30:33], v[170:173], v[242:245], v[30:33]
	v_mfma_f32_16x16x32_bf16 v[26:29], v[178:181], v[242:245], v[26:29]
	v_mfma_f32_16x16x32_bf16 v[70:73], v[182:185], v[208:211], v[70:73]
	v_mfma_f32_16x16x32_bf16 v[62:65], v[190:193], v[208:211], v[62:65]
	v_mfma_f32_16x16x32_bf16 v[54:57], v[182:185], v[216:219], v[54:57]
	v_mfma_f32_16x16x32_bf16 v[50:53], v[190:193], v[216:219], v[50:53]
	v_mfma_f32_16x16x32_bf16 v[38:41], v[182:185], v[224:227], v[38:41]
	v_mfma_f32_16x16x32_bf16 v[34:37], v[190:193], v[224:227], v[34:37]
	v_mfma_f32_16x16x32_bf16 v[22:25], v[182:185], v[238:241], v[22:25]
	v_mfma_f32_16x16x32_bf16 v[18:21], v[190:193], v[238:241], v[18:21]
	v_mfma_f32_16x16x32_bf16 v[70:73], v[186:189], v[212:215], v[70:73]
	v_mfma_f32_16x16x32_bf16 v[62:65], v[204:207], v[212:215], v[62:65]
	v_mfma_f32_16x16x32_bf16 v[54:57], v[186:189], v[220:223], v[54:57]
	v_mfma_f32_16x16x32_bf16 v[50:53], v[204:207], v[220:223], v[50:53]
	v_mfma_f32_16x16x32_bf16 v[38:41], v[186:189], v[228:231], v[38:41]
	v_mfma_f32_16x16x32_bf16 v[34:37], v[204:207], v[228:231], v[34:37]
	v_mfma_f32_16x16x32_bf16 v[22:25], v[186:189], v[242:245], v[22:25]
	v_mfma_f32_16x16x32_bf16 v[18:21], v[204:207], v[242:245], v[18:21]
	s_setprio 0
	s_barrier
	s_add_i32 s42, s42, 2
	s_add_u32 s44, s44, 0x100
	s_addc_u32 s45, s45, 0
	s_add_u32 s64, s64, 0x100
	s_addc_u32 s65, s65, 0
	s_cmp_gt_u32 s42, 13
	s_cbranch_scc0 .LBB0_596
	s_and_b64 vcc, exec, s[74:75]
	s_cbranch_vccz .LBB0_600
	s_barrier
	s_and_b64 s[44:45], s[34:35], s[38:39]
	s_and_saveexec_b64 s[76:77], s[44:45]
	s_cbranch_execnz .LBB0_601

.LBB0_896:
	s_add_u32 s25, s18, s24
	s_addc_u32 s30, s19, 0
	s_add_u32 s28, s25, 0x100
	s_addc_u32 s29, s30, 0
	s_and_b64 s[26:27], s[22:23], exec
	s_cselect_b32 s27, s13, s29
	s_cselect_b32 s26, s12, s28
	s_add_u32 s24, s16, s24
	s_addc_u32 s28, s17, 0
	s_add_u32 s24, s24, 0x100
	s_addc_u32 s28, s28, 0
	s_and_b64 s[22:23], s[22:23], exec
	v_add_u32_e32 v140, s38, v143
	s_cselect_b32 s29, s62, s28
	s_cselect_b32 s28, s63, s24
	s_add_u32 s34, s25, 0x2c0080
	ds_read_b128 v[136:139], v140
	ds_read_b128 v[158:161], v140 offset:1024
	ds_read_b128 v[162:165], v140 offset:2048
	ds_read_b128 v[166:169], v140 offset:3072
	v_add_u32_e32 v140, s41, v143
	s_addc_u32 s35, s30, 0
	s_add_i32 m0, s44, 0xc000
	s_add_i32 s64, s44, 0xe000
	ds_read_b128 v[170:173], v140
	ds_read_b128 v[174:177], v140 offset:1024
	ds_read_b128 v[178:181], v140 offset:2048
	ds_read_b128 v[182:185], v140 offset:3072
	s_add_u32 s30, s28, 0x40000
	s_addc_u32 s31, s29, 0
	s_add_u32 s24, s26, 0x2c0000
	s_addc_u32 s25, s27, 0
	s_add_u32 s22, s28, 0x40080
	s_addc_u32 s23, s29, 0
	v_lshl_add_u64 v[140:141], s[34:35], 0, v[134:135]
	ds_read_b128 v[186:189], v155
	ds_read_b128 v[190:193], v155 offset:1024
	ds_read_b128 v[204:207], v155 offset:2048
	ds_read_b128 v[208:211], v155 offset:3072
	ds_read_b128 v[212:215], v155 offset:4096
	ds_read_b128 v[216:219], v155 offset:5120
	ds_read_b128 v[220:223], v155 offset:6144
	ds_read_b128 v[224:227], v155 offset:7168
	global_load_lds_dwordx4 v[140:141], off
	v_lshl_add_u64 v[140:141], s[34:35], 0, v[132:133]
	s_mov_b32 m0, s64
	s_nop 0
	global_load_lds_dwordx4 v[140:141], off
	s_waitcnt vmcnt(8)
	s_waitcnt lgkmcnt(0)
	s_barrier
	s_setprio 1
	s_waitcnt lgkmcnt(0)
	v_mfma_f32_16x16x32_bf16 v[126:129], v[136:139], v[186:189], v[126:129]
	v_mfma_f32_16x16x32_bf16 v[122:125], v[162:165], v[186:189], v[122:125]
	v_mfma_f32_16x16x32_bf16 v[110:113], v[136:139], v[204:207], v[110:113]
	v_mfma_f32_16x16x32_bf16 v[106:109], v[162:165], v[204:207], v[106:109]
	v_mfma_f32_16x16x32_bf16 v[94:97], v[136:139], v[212:215], v[94:97]
	v_mfma_f32_16x16x32_bf16 v[90:93], v[162:165], v[212:215], v[90:93]
	v_mfma_f32_16x16x32_bf16 v[78:81], v[136:139], v[220:223], v[78:81]
	v_mfma_f32_16x16x32_bf16 v[74:77], v[162:165], v[220:223], v[74:77]
	v_mfma_f32_16x16x32_bf16 v[126:129], v[158:161], v[190:193], v[126:129]
	v_mfma_f32_16x16x32_bf16 v[122:125], v[166:169], v[190:193], v[122:125]
	v_mfma_f32_16x16x32_bf16 v[110:113], v[158:161], v[208:211], v[110:113]
	v_mfma_f32_16x16x32_bf16 v[106:109], v[166:169], v[208:211], v[106:109]
	v_mfma_f32_16x16x32_bf16 v[94:97], v[158:161], v[216:219], v[94:97]
	v_mfma_f32_16x16x32_bf16 v[90:93], v[166:169], v[216:219], v[90:93]
	v_mfma_f32_16x16x32_bf16 v[78:81], v[158:161], v[224:227], v[78:81]
	v_mfma_f32_16x16x32_bf16 v[74:77], v[166:169], v[224:227], v[74:77]
	v_mfma_f32_16x16x32_bf16 v[118:121], v[170:173], v[186:189], v[118:121]
	v_mfma_f32_16x16x32_bf16 v[114:117], v[178:181], v[186:189], v[114:117]
	v_mfma_f32_16x16x32_bf16 v[102:105], v[170:173], v[204:207], v[102:105]
	v_mfma_f32_16x16x32_bf16 v[98:101], v[178:181], v[204:207], v[98:101]
	v_mfma_f32_16x16x32_bf16 v[86:89], v[170:173], v[212:215], v[86:89]
	v_mfma_f32_16x16x32_bf16 v[82:85], v[178:181], v[212:215], v[82:85]
	v_mfma_f32_16x16x32_bf16 v[70:73], v[170:173], v[220:223], v[70:73]
	v_mfma_f32_16x16x32_bf16 v[66:69], v[178:181], v[220:223], v[66:69]
	v_mfma_f32_16x16x32_bf16 v[118:121], v[174:177], v[190:193], v[118:121]
	v_mfma_f32_16x16x32_bf16 v[114:117], v[182:185], v[190:193], v[114:117]
	v_mfma_f32_16x16x32_bf16 v[102:105], v[174:177], v[208:211], v[102:105]
	v_mfma_f32_16x16x32_bf16 v[98:101], v[182:185], v[208:211], v[98:101]
	v_mfma_f32_16x16x32_bf16 v[86:89], v[174:177], v[216:219], v[86:89]
	v_mfma_f32_16x16x32_bf16 v[82:85], v[182:185], v[216:219], v[82:85]
	v_mfma_f32_16x16x32_bf16 v[70:73], v[174:177], v[224:227], v[70:73]
	v_mfma_f32_16x16x32_bf16 v[66:69], v[182:185], v[224:227], v[66:69]
	s_setprio 0
	s_barrier
	s_mov_b32 m0, s39
	v_lshl_add_u64 v[140:141], s[28:29], 0, v[0:1]
	ds_read_b128 v[186:189], v155 offset:16384
	ds_read_b128 v[190:193], v155 offset:17408
	ds_read_b128 v[204:207], v155 offset:18432
	ds_read_b128 v[208:211], v155 offset:19456
	ds_read_b128 v[212:215], v155 offset:20480
	ds_read_b128 v[216:219], v155 offset:21504
	ds_read_b128 v[220:223], v155 offset:22528
	ds_read_b128 v[224:227], v155 offset:23552
	global_load_lds_dwordx4 v[140:141], off
	v_lshl_add_u64 v[200:201], s[28:29], 0, v[130:131]
	s_mov_b32 m0, s40
	v_lshl_add_u64 v[228:229], s[30:31], 0, v[0:1]
	global_load_lds_dwordx4 v[200:201], off
	s_mov_b32 m0, s42
	v_lshl_add_u64 v[230:231], s[26:27], 0, v[132:133]
	global_load_lds_dwordx4 v[228:229], off
	v_lshl_add_u64 v[228:229], s[30:31], 0, v[130:131]
	s_mov_b32 m0, s43
	s_nop 0
	global_load_lds_dwordx4 v[228:229], off
	v_lshl_add_u64 v[228:229], s[26:27], 0, v[134:135]
	s_mov_b32 m0, s44
	s_nop 0
	global_load_lds_dwordx4 v[228:229], off
	s_mov_b32 m0, s45
	s_nop 0
	global_load_lds_dwordx4 v[230:231], off
	s_waitcnt vmcnt(8)
	s_waitcnt lgkmcnt(0)
	s_barrier
	s_setprio 1
	s_waitcnt lgkmcnt(0)
	v_mfma_f32_16x16x32_bf16 v[62:65], v[136:139], v[186:189], v[62:65]
	v_mfma_f32_16x16x32_bf16 v[58:61], v[162:165], v[186:189], v[58:61]
	v_mfma_f32_16x16x32_bf16 v[46:49], v[136:139], v[204:207], v[46:49]
	v_mfma_f32_16x16x32_bf16 v[42:45], v[162:165], v[204:207], v[42:45]
	v_mfma_f32_16x16x32_bf16 v[30:33], v[136:139], v[212:215], v[30:33]
	v_mfma_f32_16x16x32_bf16 v[26:29], v[162:165], v[212:215], v[26:29]
	v_mfma_f32_16x16x32_bf16 v[14:17], v[136:139], v[220:223], v[14:17]
	v_mfma_f32_16x16x32_bf16 v[10:13], v[162:165], v[220:223], v[10:13]
	v_mfma_f32_16x16x32_bf16 v[62:65], v[158:161], v[190:193], v[62:65]
	v_mfma_f32_16x16x32_bf16 v[58:61], v[166:169], v[190:193], v[58:61]
	v_mfma_f32_16x16x32_bf16 v[46:49], v[158:161], v[208:211], v[46:49]
	v_mfma_f32_16x16x32_bf16 v[42:45], v[166:169], v[208:211], v[42:45]
	v_mfma_f32_16x16x32_bf16 v[30:33], v[158:161], v[216:219], v[30:33]
	v_mfma_f32_16x16x32_bf16 v[26:29], v[166:169], v[216:219], v[26:29]
	v_mfma_f32_16x16x32_bf16 v[14:17], v[158:161], v[224:227], v[14:17]
	v_mfma_f32_16x16x32_bf16 v[10:13], v[166:169], v[224:227], v[10:13]
	v_mfma_f32_16x16x32_bf16 v[54:57], v[170:173], v[186:189], v[54:57]
	v_mfma_f32_16x16x32_bf16 v[50:53], v[178:181], v[186:189], v[50:53]
	v_mfma_f32_16x16x32_bf16 v[38:41], v[170:173], v[204:207], v[38:41]
	v_mfma_f32_16x16x32_bf16 v[34:37], v[178:181], v[204:207], v[34:37]
	v_mfma_f32_16x16x32_bf16 v[22:25], v[170:173], v[212:215], v[22:25]
	v_mfma_f32_16x16x32_bf16 v[18:21], v[178:181], v[212:215], v[18:21]
	v_mfma_f32_16x16x32_bf16 v[6:9], v[170:173], v[220:223], v[6:9]
	v_mfma_f32_16x16x32_bf16 v[2:5], v[178:181], v[220:223], v[2:5]
	v_mfma_f32_16x16x32_bf16 v[54:57], v[174:177], v[190:193], v[54:57]
	v_mfma_f32_16x16x32_bf16 v[50:53], v[182:185], v[190:193], v[50:53]
	v_mfma_f32_16x16x32_bf16 v[38:41], v[174:177], v[208:211], v[38:41]
	v_mfma_f32_16x16x32_bf16 v[34:37], v[182:185], v[208:211], v[34:37]
	v_mfma_f32_16x16x32_bf16 v[22:25], v[174:177], v[216:219], v[22:25]
	v_mfma_f32_16x16x32_bf16 v[18:21], v[182:185], v[216:219], v[18:21]
	v_mfma_f32_16x16x32_bf16 v[6:9], v[174:177], v[224:227], v[6:9]
	v_mfma_f32_16x16x32_bf16 v[2:5], v[182:185], v[224:227], v[2:5]
	s_setprio 0
	s_barrier
	v_add_u32_e32 v157, s48, v143
	ds_read_b128 v[136:139], v157
	ds_read_b128 v[158:161], v157 offset:1024
	ds_read_b128 v[162:165], v157 offset:2048
	ds_read_b128 v[166:169], v157 offset:3072
	v_add_u32_e32 v157, s53, v143
	ds_read_b128 v[170:173], v157
	ds_read_b128 v[174:177], v157 offset:1024
	ds_read_b128 v[178:181], v157 offset:2048
	ds_read_b128 v[182:185], v157 offset:3072
	s_mov_b32 m0, s46
	v_lshl_add_u64 v[232:233], s[24:25], 0, v[134:135]
	ds_read_b128 v[186:189], v155 offset:32768
	ds_read_b128 v[190:193], v155 offset:33792
	ds_read_b128 v[204:207], v155 offset:34816
	ds_read_b128 v[208:211], v155 offset:35840
	ds_read_b128 v[212:215], v155 offset:36864
	ds_read_b128 v[216:219], v155 offset:37888
	ds_read_b128 v[220:223], v155 offset:38912
	ds_read_b128 v[224:227], v155 offset:39936
	global_load_lds_dwordx4 v[232:233], off
	v_lshl_add_u64 v[232:233], s[24:25], 0, v[132:133]
	s_mov_b32 m0, s47
	s_nop 0
	global_load_lds_dwordx4 v[232:233], off
	s_waitcnt vmcnt(8)
	s_waitcnt lgkmcnt(0)
	s_barrier
	s_setprio 1
	s_waitcnt lgkmcnt(0)
	v_mfma_f32_16x16x32_bf16 v[126:129], v[136:139], v[186:189], v[126:129]
	v_mfma_f32_16x16x32_bf16 v[122:125], v[162:165], v[186:189], v[122:125]
	v_mfma_f32_16x16x32_bf16 v[110:113], v[136:139], v[204:207], v[110:113]
	v_mfma_f32_16x16x32_bf16 v[106:109], v[162:165], v[204:207], v[106:109]
	v_mfma_f32_16x16x32_bf16 v[94:97], v[136:139], v[212:215], v[94:97]
	v_mfma_f32_16x16x32_bf16 v[90:93], v[162:165], v[212:215], v[90:93]
	v_mfma_f32_16x16x32_bf16 v[78:81], v[136:139], v[220:223], v[78:81]
	v_mfma_f32_16x16x32_bf16 v[74:77], v[162:165], v[220:223], v[74:77]
	v_mfma_f32_16x16x32_bf16 v[126:129], v[158:161], v[190:193], v[126:129]
	v_mfma_f32_16x16x32_bf16 v[122:125], v[166:169], v[190:193], v[122:125]
	v_mfma_f32_16x16x32_bf16 v[110:113], v[158:161], v[208:211], v[110:113]
	v_mfma_f32_16x16x32_bf16 v[106:109], v[166:169], v[208:211], v[106:109]
	v_mfma_f32_16x16x32_bf16 v[94:97], v[158:161], v[216:219], v[94:97]
	v_mfma_f32_16x16x32_bf16 v[90:93], v[166:169], v[216:219], v[90:93]
	v_mfma_f32_16x16x32_bf16 v[78:81], v[158:161], v[224:227], v[78:81]
	v_mfma_f32_16x16x32_bf16 v[74:77], v[166:169], v[224:227], v[74:77]
	v_mfma_f32_16x16x32_bf16 v[118:121], v[170:173], v[186:189], v[118:121]
	v_mfma_f32_16x16x32_bf16 v[114:117], v[178:181], v[186:189], v[114:117]
	v_mfma_f32_16x16x32_bf16 v[102:105], v[170:173], v[204:207], v[102:105]
	v_mfma_f32_16x16x32_bf16 v[98:101], v[178:181], v[204:207], v[98:101]
	v_mfma_f32_16x16x32_bf16 v[86:89], v[170:173], v[212:215], v[86:89]
	v_mfma_f32_16x16x32_bf16 v[82:85], v[178:181], v[212:215], v[82:85]
	v_mfma_f32_16x16x32_bf16 v[70:73], v[170:173], v[220:223], v[70:73]
	v_mfma_f32_16x16x32_bf16 v[66:69], v[178:181], v[220:223], v[66:69]
	v_mfma_f32_16x16x32_bf16 v[118:121], v[174:177], v[190:193], v[118:121]
	v_mfma_f32_16x16x32_bf16 v[114:117], v[182:185], v[190:193], v[114:117]
	v_mfma_f32_16x16x32_bf16 v[102:105], v[174:177], v[208:211], v[102:105]
	v_mfma_f32_16x16x32_bf16 v[98:101], v[182:185], v[208:211], v[98:101]
	v_mfma_f32_16x16x32_bf16 v[86:89], v[174:177], v[216:219], v[86:89]
	v_mfma_f32_16x16x32_bf16 v[82:85], v[182:185], v[216:219], v[82:85]
	v_mfma_f32_16x16x32_bf16 v[70:73], v[174:177], v[224:227], v[70:73]
	v_mfma_f32_16x16x32_bf16 v[66:69], v[182:185], v[224:227], v[66:69]
	s_setprio 0
	s_barrier
	s_mov_b32 m0, s49
	v_lshl_add_u64 v[140:141], v[140:141], 0, s[80:81]
	ds_read_b128 v[186:189], v155 offset:49152
	ds_read_b128 v[190:193], v155 offset:50176
	ds_read_b128 v[204:207], v155 offset:51200
	ds_read_b128 v[208:211], v155 offset:52224
	ds_read_b128 v[212:215], v155 offset:53248
	ds_read_b128 v[216:219], v155 offset:54272
	ds_read_b128 v[220:223], v155 offset:55296
	ds_read_b128 v[224:227], v155 offset:56320
	global_load_lds_dwordx4 v[140:141], off
	v_lshl_add_u64 v[140:141], v[200:201], 0, s[80:81]
	s_mov_b32 m0, s50
	s_nop 0
	global_load_lds_dwordx4 v[140:141], off
	v_lshl_add_u64 v[140:141], s[22:23], 0, v[0:1]
	s_mov_b32 m0, s54
	s_nop 0
	global_load_lds_dwordx4 v[140:141], off
	v_lshl_add_u64 v[140:141], s[22:23], 0, v[130:131]
	s_mov_b32 m0, s55
	s_nop 0
	global_load_lds_dwordx4 v[140:141], off
	v_lshl_add_u64 v[140:141], v[228:229], 0, s[80:81]
	s_mov_b32 m0, s51
	s_nop 0
	global_load_lds_dwordx4 v[140:141], off
	v_lshl_add_u64 v[140:141], v[230:231], 0, s[80:81]
	s_mov_b32 m0, s52
	s_nop 0
	global_load_lds_dwordx4 v[140:141], off
	s_waitcnt vmcnt(8)
	s_waitcnt lgkmcnt(0)
	s_barrier
	s_setprio 1
	s_waitcnt lgkmcnt(0)
	v_mfma_f32_16x16x32_bf16 v[62:65], v[136:139], v[186:189], v[62:65]
	v_mfma_f32_16x16x32_bf16 v[58:61], v[162:165], v[186:189], v[58:61]
	v_mfma_f32_16x16x32_bf16 v[46:49], v[136:139], v[204:207], v[46:49]
	v_mfma_f32_16x16x32_bf16 v[42:45], v[162:165], v[204:207], v[42:45]
	v_mfma_f32_16x16x32_bf16 v[30:33], v[136:139], v[212:215], v[30:33]
	v_mfma_f32_16x16x32_bf16 v[26:29], v[162:165], v[212:215], v[26:29]
	v_mfma_f32_16x16x32_bf16 v[14:17], v[136:139], v[220:223], v[14:17]
	v_mfma_f32_16x16x32_bf16 v[10:13], v[162:165], v[220:223], v[10:13]
	v_mfma_f32_16x16x32_bf16 v[62:65], v[158:161], v[190:193], v[62:65]
	v_mfma_f32_16x16x32_bf16 v[58:61], v[166:169], v[190:193], v[58:61]
	v_mfma_f32_16x16x32_bf16 v[46:49], v[158:161], v[208:211], v[46:49]
	v_mfma_f32_16x16x32_bf16 v[42:45], v[166:169], v[208:211], v[42:45]
	v_mfma_f32_16x16x32_bf16 v[30:33], v[158:161], v[216:219], v[30:33]
	v_mfma_f32_16x16x32_bf16 v[26:29], v[166:169], v[216:219], v[26:29]
	v_mfma_f32_16x16x32_bf16 v[14:17], v[158:161], v[224:227], v[14:17]
	v_mfma_f32_16x16x32_bf16 v[10:13], v[166:169], v[224:227], v[10:13]
	v_mfma_f32_16x16x32_bf16 v[54:57], v[170:173], v[186:189], v[54:57]
	v_mfma_f32_16x16x32_bf16 v[50:53], v[178:181], v[186:189], v[50:53]
	v_mfma_f32_16x16x32_bf16 v[38:41], v[170:173], v[204:207], v[38:41]
	v_mfma_f32_16x16x32_bf16 v[34:37], v[178:181], v[204:207], v[34:37]
	v_mfma_f32_16x16x32_bf16 v[22:25], v[170:173], v[212:215], v[22:25]
	v_mfma_f32_16x16x32_bf16 v[18:21], v[178:181], v[212:215], v[18:21]
	v_mfma_f32_16x16x32_bf16 v[6:9], v[170:173], v[220:223], v[6:9]
	v_mfma_f32_16x16x32_bf16 v[2:5], v[178:181], v[220:223], v[2:5]
	v_mfma_f32_16x16x32_bf16 v[54:57], v[174:177], v[190:193], v[54:57]
	v_mfma_f32_16x16x32_bf16 v[50:53], v[182:185], v[190:193], v[50:53]
	v_mfma_f32_16x16x32_bf16 v[38:41], v[174:177], v[208:211], v[38:41]
	v_mfma_f32_16x16x32_bf16 v[34:37], v[182:185], v[208:211], v[34:37]
	v_mfma_f32_16x16x32_bf16 v[22:25], v[174:177], v[216:219], v[22:25]
	v_mfma_f32_16x16x32_bf16 v[18:21], v[182:185], v[216:219], v[18:21]
	v_mfma_f32_16x16x32_bf16 v[6:9], v[174:177], v[224:227], v[6:9]
	v_mfma_f32_16x16x32_bf16 v[2:5], v[182:185], v[224:227], v[2:5]
	s_setprio 0
	s_barrier
	s_movk_i32 s24, 0x100
	s_andn2_b64 vcc, exec, s[20:21]
	s_mov_b64 s[22:23], -1
	s_mov_b64 s[20:21], 0
	s_cbranch_vccz .LBB0_896
	s_and_b64 vcc, exec, s[8:9]
	s_cbranch_vccz .LBB0_899
	s_barrier

.LBB0_1010:
	s_add_u32 s36, s22, s17
	s_addc_u32 s37, s23, 0
	s_add_u32 s30, s36, 0x100
	s_addc_u32 s31, s37, 0
	s_and_b64 s[28:29], s[26:27], exec
	s_cselect_b32 s31, s15, s31
	s_cselect_b32 s30, s14, s30
	s_add_u32 s17, s20, s17
	s_addc_u32 s28, s21, 0
	s_add_u32 s17, s17, 0x100
	s_addc_u32 s28, s28, 0
	s_and_b64 s[26:27], s[26:27], exec
	s_cselect_b32 s35, s19, s28
	s_cselect_b32 s34, s18, s17
	s_add_u32 s38, s36, 0x40080
	v_add_u32_e32 v86, s5, v223
	v_add_u32_e32 v158, s53, v223
	s_addc_u32 s39, s37, 0
	s_add_i32 m0, s56, 0xc000
	s_add_i32 s17, s56, 0xe000
	ds_read_b128 v[70:73], v86
	ds_read_b128 v[78:81], v86 offset:1024
	ds_read_b128 v[82:85], v86 offset:2048
	ds_read_b128 v[86:89], v86 offset:3072
	ds_read_b128 v[146:149], v158
	ds_read_b128 v[150:153], v158 offset:1024
	ds_read_b128 v[154:157], v158 offset:2048
	ds_read_b128 v[158:161], v158 offset:3072
	s_add_u32 s36, s34, 0x10000
	s_addc_u32 s37, s35, 0
	s_add_u32 s28, s30, 0x40000
	s_addc_u32 s29, s31, 0
	s_add_u32 s26, s34, 0x10080
	s_addc_u32 s27, s35, 0
	v_lshl_add_u64 v[200:201], s[38:39], 0, v[208:209]
	ds_read_b128 v[162:165], v225
	ds_read_b128 v[166:169], v225 offset:1024
	ds_read_b128 v[170:173], v225 offset:2048
	ds_read_b128 v[174:177], v225 offset:3072
	ds_read_b128 v[178:181], v225 offset:4096
	ds_read_b128 v[182:185], v225 offset:5120
	ds_read_b128 v[186:189], v225 offset:6144
	ds_read_b128 v[190:193], v225 offset:7168
	global_load_lds_dwordx4 v[200:201], off
	v_lshl_add_u64 v[200:201], s[38:39], 0, v[206:207]
	s_mov_b32 m0, s17
	s_nop 0
	global_load_lds_dwordx4 v[200:201], off
	s_waitcnt vmcnt(8)
	s_waitcnt lgkmcnt(0)
	s_barrier
	s_setprio 1
	s_waitcnt lgkmcnt(0)
	v_mfma_f32_16x16x32_bf16 v[142:145], v[70:73], v[162:165], v[142:145]
	v_mfma_f32_16x16x32_bf16 v[138:141], v[82:85], v[162:165], v[138:141]
	v_mfma_f32_16x16x32_bf16 v[126:129], v[70:73], v[170:173], v[126:129]
	v_mfma_f32_16x16x32_bf16 v[122:125], v[82:85], v[170:173], v[122:125]
	v_mfma_f32_16x16x32_bf16 v[110:113], v[70:73], v[178:181], v[110:113]
	v_mfma_f32_16x16x32_bf16 v[106:109], v[82:85], v[178:181], v[106:109]
	v_mfma_f32_16x16x32_bf16 v[94:97], v[70:73], v[186:189], v[94:97]
	v_mfma_f32_16x16x32_bf16 v[90:93], v[82:85], v[186:189], v[90:93]
	v_mfma_f32_16x16x32_bf16 v[142:145], v[78:81], v[166:169], v[142:145]
	v_mfma_f32_16x16x32_bf16 v[138:141], v[86:89], v[166:169], v[138:141]
	v_mfma_f32_16x16x32_bf16 v[126:129], v[78:81], v[174:177], v[126:129]
	v_mfma_f32_16x16x32_bf16 v[122:125], v[86:89], v[174:177], v[122:125]
	v_mfma_f32_16x16x32_bf16 v[110:113], v[78:81], v[182:185], v[110:113]
	v_mfma_f32_16x16x32_bf16 v[106:109], v[86:89], v[182:185], v[106:109]
	v_mfma_f32_16x16x32_bf16 v[94:97], v[78:81], v[190:193], v[94:97]
	v_mfma_f32_16x16x32_bf16 v[90:93], v[86:89], v[190:193], v[90:93]
	v_mfma_f32_16x16x32_bf16 v[134:137], v[146:149], v[162:165], v[134:137]
	v_mfma_f32_16x16x32_bf16 v[130:133], v[154:157], v[162:165], v[130:133]
	v_mfma_f32_16x16x32_bf16 v[118:121], v[146:149], v[170:173], v[118:121]
	v_mfma_f32_16x16x32_bf16 v[114:117], v[154:157], v[170:173], v[114:117]
	v_mfma_f32_16x16x32_bf16 v[102:105], v[146:149], v[178:181], v[102:105]
	v_mfma_f32_16x16x32_bf16 v[98:101], v[154:157], v[178:181], v[98:101]
	v_mfma_f32_16x16x32_bf16 v[74:77], v[146:149], v[186:189], v[74:77]
	v_mfma_f32_16x16x32_bf16 v[66:69], v[154:157], v[186:189], v[66:69]
	v_mfma_f32_16x16x32_bf16 v[134:137], v[150:153], v[166:169], v[134:137]
	v_mfma_f32_16x16x32_bf16 v[130:133], v[158:161], v[166:169], v[130:133]
	v_mfma_f32_16x16x32_bf16 v[118:121], v[150:153], v[174:177], v[118:121]
	v_mfma_f32_16x16x32_bf16 v[114:117], v[158:161], v[174:177], v[114:117]
	v_mfma_f32_16x16x32_bf16 v[102:105], v[150:153], v[182:185], v[102:105]
	v_mfma_f32_16x16x32_bf16 v[98:101], v[158:161], v[182:185], v[98:101]
	v_mfma_f32_16x16x32_bf16 v[74:77], v[150:153], v[190:193], v[74:77]
	v_mfma_f32_16x16x32_bf16 v[66:69], v[158:161], v[190:193], v[66:69]
	s_setprio 0
	s_barrier
	s_mov_b32 m0, s51
	v_lshl_add_u64 v[200:201], s[34:35], 0, v[0:1]
	ds_read_b128 v[162:165], v225 offset:16384
	ds_read_b128 v[166:169], v225 offset:17408
	ds_read_b128 v[170:173], v225 offset:18432
	ds_read_b128 v[174:177], v225 offset:19456
	ds_read_b128 v[178:181], v225 offset:20480
	ds_read_b128 v[182:185], v225 offset:21504
	ds_read_b128 v[186:189], v225 offset:22528
	ds_read_b128 v[190:193], v225 offset:23552
	global_load_lds_dwordx4 v[200:201], off
	v_lshl_add_u64 v[210:211], s[34:35], 0, v[204:205]
	s_mov_b32 m0, s52
	v_lshl_add_u64 v[212:213], s[36:37], 0, v[0:1]
	global_load_lds_dwordx4 v[210:211], off
	s_mov_b32 m0, s54
	v_lshl_add_u64 v[214:215], s[30:31], 0, v[206:207]
	global_load_lds_dwordx4 v[212:213], off
	v_lshl_add_u64 v[212:213], s[36:37], 0, v[204:205]
	s_mov_b32 m0, s55
	s_nop 0
	global_load_lds_dwordx4 v[212:213], off
	v_lshl_add_u64 v[212:213], s[30:31], 0, v[208:209]
	s_mov_b32 m0, s56
	s_nop 0
	global_load_lds_dwordx4 v[212:213], off
	s_mov_b32 m0, s57
	s_nop 0
	global_load_lds_dwordx4 v[214:215], off
	s_waitcnt vmcnt(8)
	s_waitcnt lgkmcnt(0)
	s_barrier
	s_setprio 1
	s_waitcnt lgkmcnt(0)
	v_mfma_f32_16x16x32_bf16 v[62:65], v[70:73], v[162:165], v[62:65]
	v_mfma_f32_16x16x32_bf16 v[58:61], v[82:85], v[162:165], v[58:61]
	v_mfma_f32_16x16x32_bf16 v[46:49], v[70:73], v[170:173], v[46:49]
	v_mfma_f32_16x16x32_bf16 v[42:45], v[82:85], v[170:173], v[42:45]
	v_mfma_f32_16x16x32_bf16 v[30:33], v[70:73], v[178:181], v[30:33]
	v_mfma_f32_16x16x32_bf16 v[26:29], v[82:85], v[178:181], v[26:29]
	v_mfma_f32_16x16x32_bf16 v[14:17], v[70:73], v[186:189], v[14:17]
	v_mfma_f32_16x16x32_bf16 v[10:13], v[82:85], v[186:189], v[10:13]
	v_mfma_f32_16x16x32_bf16 v[62:65], v[78:81], v[166:169], v[62:65]
	v_mfma_f32_16x16x32_bf16 v[58:61], v[86:89], v[166:169], v[58:61]
	v_mfma_f32_16x16x32_bf16 v[46:49], v[78:81], v[174:177], v[46:49]
	v_mfma_f32_16x16x32_bf16 v[42:45], v[86:89], v[174:177], v[42:45]
	v_mfma_f32_16x16x32_bf16 v[30:33], v[78:81], v[182:185], v[30:33]
	v_mfma_f32_16x16x32_bf16 v[26:29], v[86:89], v[182:185], v[26:29]
	v_mfma_f32_16x16x32_bf16 v[14:17], v[78:81], v[190:193], v[14:17]
	v_mfma_f32_16x16x32_bf16 v[10:13], v[86:89], v[190:193], v[10:13]
	v_mfma_f32_16x16x32_bf16 v[54:57], v[146:149], v[162:165], v[54:57]
	v_mfma_f32_16x16x32_bf16 v[50:53], v[154:157], v[162:165], v[50:53]
	v_mfma_f32_16x16x32_bf16 v[38:41], v[146:149], v[170:173], v[38:41]
	v_mfma_f32_16x16x32_bf16 v[34:37], v[154:157], v[170:173], v[34:37]
	v_mfma_f32_16x16x32_bf16 v[22:25], v[146:149], v[178:181], v[22:25]
	v_mfma_f32_16x16x32_bf16 v[18:21], v[154:157], v[178:181], v[18:21]
	v_mfma_f32_16x16x32_bf16 v[6:9], v[146:149], v[186:189], v[6:9]
	v_mfma_f32_16x16x32_bf16 v[2:5], v[154:157], v[186:189], v[2:5]
	v_mfma_f32_16x16x32_bf16 v[54:57], v[150:153], v[166:169], v[54:57]
	v_mfma_f32_16x16x32_bf16 v[50:53], v[158:161], v[166:169], v[50:53]
	v_mfma_f32_16x16x32_bf16 v[38:41], v[150:153], v[174:177], v[38:41]
	v_mfma_f32_16x16x32_bf16 v[34:37], v[158:161], v[174:177], v[34:37]
	v_mfma_f32_16x16x32_bf16 v[22:25], v[150:153], v[182:185], v[22:25]
	v_mfma_f32_16x16x32_bf16 v[18:21], v[158:161], v[182:185], v[18:21]
	v_mfma_f32_16x16x32_bf16 v[6:9], v[150:153], v[190:193], v[6:9]
	v_mfma_f32_16x16x32_bf16 v[2:5], v[158:161], v[190:193], v[2:5]
	s_setprio 0
	s_barrier
	v_add_u32_e32 v86, s66, v223
	v_add_u32_e32 v158, s71, v223
	ds_read_b128 v[70:73], v86
	ds_read_b128 v[78:81], v86 offset:1024
	ds_read_b128 v[82:85], v86 offset:2048
	ds_read_b128 v[86:89], v86 offset:3072
	ds_read_b128 v[146:149], v158
	ds_read_b128 v[150:153], v158 offset:1024
	ds_read_b128 v[154:157], v158 offset:2048
	ds_read_b128 v[158:161], v158 offset:3072
	s_mov_b32 m0, s58
	v_lshl_add_u64 v[216:217], s[28:29], 0, v[208:209]
	ds_read_b128 v[162:165], v225 offset:32768
	ds_read_b128 v[166:169], v225 offset:33792
	ds_read_b128 v[170:173], v225 offset:34816
	ds_read_b128 v[174:177], v225 offset:35840
	ds_read_b128 v[178:181], v225 offset:36864
	ds_read_b128 v[182:185], v225 offset:37888
	ds_read_b128 v[186:189], v225 offset:38912
	ds_read_b128 v[190:193], v225 offset:39936
	global_load_lds_dwordx4 v[216:217], off
	v_lshl_add_u64 v[216:217], s[28:29], 0, v[206:207]
	s_mov_b32 m0, s59
	s_nop 0
	global_load_lds_dwordx4 v[216:217], off
	s_waitcnt vmcnt(8)
	s_waitcnt lgkmcnt(0)
	s_barrier
	s_setprio 1
	s_waitcnt lgkmcnt(0)
	v_mfma_f32_16x16x32_bf16 v[142:145], v[70:73], v[162:165], v[142:145]
	v_mfma_f32_16x16x32_bf16 v[138:141], v[82:85], v[162:165], v[138:141]
	v_mfma_f32_16x16x32_bf16 v[126:129], v[70:73], v[170:173], v[126:129]
	v_mfma_f32_16x16x32_bf16 v[122:125], v[82:85], v[170:173], v[122:125]
	v_mfma_f32_16x16x32_bf16 v[110:113], v[70:73], v[178:181], v[110:113]
	v_mfma_f32_16x16x32_bf16 v[106:109], v[82:85], v[178:181], v[106:109]
	v_mfma_f32_16x16x32_bf16 v[94:97], v[70:73], v[186:189], v[94:97]
	v_mfma_f32_16x16x32_bf16 v[90:93], v[82:85], v[186:189], v[90:93]
	v_mfma_f32_16x16x32_bf16 v[142:145], v[78:81], v[166:169], v[142:145]
	v_mfma_f32_16x16x32_bf16 v[138:141], v[86:89], v[166:169], v[138:141]
	v_mfma_f32_16x16x32_bf16 v[126:129], v[78:81], v[174:177], v[126:129]
	v_mfma_f32_16x16x32_bf16 v[122:125], v[86:89], v[174:177], v[122:125]
	v_mfma_f32_16x16x32_bf16 v[110:113], v[78:81], v[182:185], v[110:113]
	v_mfma_f32_16x16x32_bf16 v[106:109], v[86:89], v[182:185], v[106:109]
	v_mfma_f32_16x16x32_bf16 v[94:97], v[78:81], v[190:193], v[94:97]
	v_mfma_f32_16x16x32_bf16 v[90:93], v[86:89], v[190:193], v[90:93]
	v_mfma_f32_16x16x32_bf16 v[134:137], v[146:149], v[162:165], v[134:137]
	v_mfma_f32_16x16x32_bf16 v[130:133], v[154:157], v[162:165], v[130:133]
	v_mfma_f32_16x16x32_bf16 v[118:121], v[146:149], v[170:173], v[118:121]
	v_mfma_f32_16x16x32_bf16 v[114:117], v[154:157], v[170:173], v[114:117]
	v_mfma_f32_16x16x32_bf16 v[102:105], v[146:149], v[178:181], v[102:105]
	v_mfma_f32_16x16x32_bf16 v[98:101], v[154:157], v[178:181], v[98:101]
	v_mfma_f32_16x16x32_bf16 v[74:77], v[146:149], v[186:189], v[74:77]
	v_mfma_f32_16x16x32_bf16 v[66:69], v[154:157], v[186:189], v[66:69]
	v_mfma_f32_16x16x32_bf16 v[134:137], v[150:153], v[166:169], v[134:137]
	v_mfma_f32_16x16x32_bf16 v[130:133], v[158:161], v[166:169], v[130:133]
	v_mfma_f32_16x16x32_bf16 v[118:121], v[150:153], v[174:177], v[118:121]
	v_mfma_f32_16x16x32_bf16 v[114:117], v[158:161], v[174:177], v[114:117]
	v_mfma_f32_16x16x32_bf16 v[102:105], v[150:153], v[182:185], v[102:105]
	v_mfma_f32_16x16x32_bf16 v[98:101], v[158:161], v[182:185], v[98:101]
	v_mfma_f32_16x16x32_bf16 v[74:77], v[150:153], v[190:193], v[74:77]
	v_mfma_f32_16x16x32_bf16 v[66:69], v[158:161], v[190:193], v[66:69]
	s_setprio 0
	s_barrier
	s_mov_b32 m0, s67
	v_lshl_add_u64 v[200:201], v[200:201], 0, s[80:81]
	ds_read_b128 v[162:165], v225 offset:49152
	ds_read_b128 v[166:169], v225 offset:50176
	ds_read_b128 v[170:173], v225 offset:51200
	ds_read_b128 v[174:177], v225 offset:52224
	ds_read_b128 v[178:181], v225 offset:53248
	ds_read_b128 v[182:185], v225 offset:54272
	ds_read_b128 v[186:189], v225 offset:55296
	ds_read_b128 v[190:193], v225 offset:56320
	global_load_lds_dwordx4 v[200:201], off
	v_lshl_add_u64 v[200:201], v[210:211], 0, s[80:81]
	s_mov_b32 m0, s68
	s_nop 0
	global_load_lds_dwordx4 v[200:201], off
	v_lshl_add_u64 v[200:201], s[26:27], 0, v[0:1]
	s_mov_b32 m0, s72
	s_nop 0
	global_load_lds_dwordx4 v[200:201], off
	v_lshl_add_u64 v[200:201], s[26:27], 0, v[204:205]
	s_mov_b32 m0, s73
	s_nop 0
	global_load_lds_dwordx4 v[200:201], off
	v_lshl_add_u64 v[200:201], v[212:213], 0, s[80:81]
	s_mov_b32 m0, s69
	s_nop 0
	global_load_lds_dwordx4 v[200:201], off
	v_lshl_add_u64 v[200:201], v[214:215], 0, s[80:81]
	s_mov_b32 m0, s70
	s_nop 0
	global_load_lds_dwordx4 v[200:201], off
	s_waitcnt vmcnt(8)
	s_waitcnt lgkmcnt(0)
	s_barrier
	s_setprio 1
	s_waitcnt lgkmcnt(0)
	v_mfma_f32_16x16x32_bf16 v[62:65], v[70:73], v[162:165], v[62:65]
	v_mfma_f32_16x16x32_bf16 v[58:61], v[82:85], v[162:165], v[58:61]
	v_mfma_f32_16x16x32_bf16 v[46:49], v[70:73], v[170:173], v[46:49]
	v_mfma_f32_16x16x32_bf16 v[42:45], v[82:85], v[170:173], v[42:45]
	v_mfma_f32_16x16x32_bf16 v[30:33], v[70:73], v[178:181], v[30:33]
	v_mfma_f32_16x16x32_bf16 v[26:29], v[82:85], v[178:181], v[26:29]
	v_mfma_f32_16x16x32_bf16 v[14:17], v[70:73], v[186:189], v[14:17]
	v_mfma_f32_16x16x32_bf16 v[10:13], v[82:85], v[186:189], v[10:13]
	v_mfma_f32_16x16x32_bf16 v[62:65], v[78:81], v[166:169], v[62:65]
	v_mfma_f32_16x16x32_bf16 v[58:61], v[86:89], v[166:169], v[58:61]
	v_mfma_f32_16x16x32_bf16 v[46:49], v[78:81], v[174:177], v[46:49]
	v_mfma_f32_16x16x32_bf16 v[42:45], v[86:89], v[174:177], v[42:45]
	v_mfma_f32_16x16x32_bf16 v[30:33], v[78:81], v[182:185], v[30:33]
	v_mfma_f32_16x16x32_bf16 v[26:29], v[86:89], v[182:185], v[26:29]
	v_mfma_f32_16x16x32_bf16 v[14:17], v[78:81], v[190:193], v[14:17]
	v_mfma_f32_16x16x32_bf16 v[10:13], v[86:89], v[190:193], v[10:13]
	v_mfma_f32_16x16x32_bf16 v[54:57], v[146:149], v[162:165], v[54:57]
	v_mfma_f32_16x16x32_bf16 v[50:53], v[154:157], v[162:165], v[50:53]
	v_mfma_f32_16x16x32_bf16 v[38:41], v[146:149], v[170:173], v[38:41]
	v_mfma_f32_16x16x32_bf16 v[34:37], v[154:157], v[170:173], v[34:37]
	v_mfma_f32_16x16x32_bf16 v[22:25], v[146:149], v[178:181], v[22:25]
	v_mfma_f32_16x16x32_bf16 v[18:21], v[154:157], v[178:181], v[18:21]
	v_mfma_f32_16x16x32_bf16 v[6:9], v[146:149], v[186:189], v[6:9]
	v_mfma_f32_16x16x32_bf16 v[2:5], v[154:157], v[186:189], v[2:5]
	v_mfma_f32_16x16x32_bf16 v[54:57], v[150:153], v[166:169], v[54:57]
	v_mfma_f32_16x16x32_bf16 v[50:53], v[158:161], v[166:169], v[50:53]
	v_mfma_f32_16x16x32_bf16 v[38:41], v[150:153], v[174:177], v[38:41]
	v_mfma_f32_16x16x32_bf16 v[34:37], v[158:161], v[174:177], v[34:37]
	v_mfma_f32_16x16x32_bf16 v[22:25], v[150:153], v[182:185], v[22:25]
	v_mfma_f32_16x16x32_bf16 v[18:21], v[158:161], v[182:185], v[18:21]
	v_mfma_f32_16x16x32_bf16 v[6:9], v[150:153], v[190:193], v[6:9]
	v_mfma_f32_16x16x32_bf16 v[2:5], v[158:161], v[190:193], v[2:5]
	s_setprio 0
	s_barrier
	s_movk_i32 s17, 0x100
	s_andn2_b64 vcc, exec, s[24:25]
	s_mov_b64 s[26:27], -1
	s_mov_b64 s[24:25], 0
	s_cbranch_vccz .LBB0_1010
	s_and_b64 vcc, exec, s[12:13]
	s_cbranch_vccz .LBB0_1013
	s_barrier

.LBB0_1107:
	v_add_u32_e32 v142, s50, v238
	v_add_u32_e32 v158, s53, v238
	ds_read_b128 v[130:133], v142
	ds_read_b128 v[134:137], v142 offset:1024
	ds_read_b128 v[138:141], v142 offset:2048
	ds_read_b128 v[142:145], v142 offset:3072
	ds_read_b128 v[146:149], v158
	ds_read_b128 v[150:153], v158 offset:1024
	ds_read_b128 v[154:157], v158 offset:2048
	ds_read_b128 v[158:161], v158 offset:3072
	s_add_u32 s36, s34, 0xfffc0080
	s_addc_u32 s37, s35, -1
	s_cmp_eq_u32 s74, 12
	s_cselect_b32 s39, s7, s37
	s_cselect_b32 s38, s25, s36
	s_cselect_b32 s37, s23, s73
	s_cselect_b32 s36, s31, s72
	v_lshl_add_u64 v[200:201], s[34:35], 0, v[210:211]
	s_add_i32 m0, s56, 0xc000
	ds_read_b128 v[162:165], v240
	ds_read_b128 v[166:169], v240 offset:1024
	ds_read_b128 v[170:173], v240 offset:2048
	ds_read_b128 v[174:177], v240 offset:3072
	ds_read_b128 v[178:181], v240 offset:4096
	ds_read_b128 v[182:185], v240 offset:5120
	ds_read_b128 v[186:189], v240 offset:6144
	ds_read_b128 v[190:193], v240 offset:7168
	global_load_lds_dwordx4 v[200:201], off
	v_lshl_add_u64 v[200:201], s[34:35], 0, v[212:213]
	s_add_i32 m0, s56, 0xe000
	s_nop 0
	global_load_lds_dwordx4 v[200:201], off
	s_waitcnt vmcnt(8)
	s_waitcnt lgkmcnt(0)
	s_barrier
	s_setprio 1
	s_waitcnt lgkmcnt(0)
	v_mfma_f32_16x16x32_bf16 v[126:129], v[130:133], v[162:165], v[126:129]
	v_mfma_f32_16x16x32_bf16 v[122:125], v[138:141], v[162:165], v[122:125]
	v_mfma_f32_16x16x32_bf16 v[110:113], v[130:133], v[170:173], v[110:113]
	v_mfma_f32_16x16x32_bf16 v[106:109], v[138:141], v[170:173], v[106:109]
	v_mfma_f32_16x16x32_bf16 v[94:97], v[130:133], v[178:181], v[94:97]
	v_mfma_f32_16x16x32_bf16 v[90:93], v[138:141], v[178:181], v[90:93]
	v_mfma_f32_16x16x32_bf16 v[78:81], v[130:133], v[186:189], v[78:81]
	v_mfma_f32_16x16x32_bf16 v[74:77], v[138:141], v[186:189], v[74:77]
	v_mfma_f32_16x16x32_bf16 v[126:129], v[134:137], v[166:169], v[126:129]
	v_mfma_f32_16x16x32_bf16 v[122:125], v[142:145], v[166:169], v[122:125]
	v_mfma_f32_16x16x32_bf16 v[110:113], v[134:137], v[174:177], v[110:113]
	v_mfma_f32_16x16x32_bf16 v[106:109], v[142:145], v[174:177], v[106:109]
	v_mfma_f32_16x16x32_bf16 v[94:97], v[134:137], v[182:185], v[94:97]
	v_mfma_f32_16x16x32_bf16 v[90:93], v[142:145], v[182:185], v[90:93]
	v_mfma_f32_16x16x32_bf16 v[78:81], v[134:137], v[190:193], v[78:81]
	v_mfma_f32_16x16x32_bf16 v[74:77], v[142:145], v[190:193], v[74:77]
	v_mfma_f32_16x16x32_bf16 v[118:121], v[146:149], v[162:165], v[118:121]
	v_mfma_f32_16x16x32_bf16 v[114:117], v[154:157], v[162:165], v[114:117]
	v_mfma_f32_16x16x32_bf16 v[102:105], v[146:149], v[170:173], v[102:105]
	v_mfma_f32_16x16x32_bf16 v[98:101], v[154:157], v[170:173], v[98:101]
	v_mfma_f32_16x16x32_bf16 v[86:89], v[146:149], v[178:181], v[86:89]
	v_mfma_f32_16x16x32_bf16 v[82:85], v[154:157], v[178:181], v[82:85]
	v_mfma_f32_16x16x32_bf16 v[70:73], v[146:149], v[186:189], v[70:73]
	v_mfma_f32_16x16x32_bf16 v[66:69], v[154:157], v[186:189], v[66:69]
	v_mfma_f32_16x16x32_bf16 v[118:121], v[150:153], v[166:169], v[118:121]
	v_mfma_f32_16x16x32_bf16 v[114:117], v[158:161], v[166:169], v[114:117]
	v_mfma_f32_16x16x32_bf16 v[102:105], v[150:153], v[174:177], v[102:105]
	v_mfma_f32_16x16x32_bf16 v[98:101], v[158:161], v[174:177], v[98:101]
	v_mfma_f32_16x16x32_bf16 v[86:89], v[150:153], v[182:185], v[86:89]
	v_mfma_f32_16x16x32_bf16 v[82:85], v[158:161], v[182:185], v[82:85]
	v_mfma_f32_16x16x32_bf16 v[70:73], v[150:153], v[190:193], v[70:73]
	v_mfma_f32_16x16x32_bf16 v[66:69], v[158:161], v[190:193], v[66:69]
	s_setprio 0
	s_barrier
	s_mov_b32 m0, s51
	v_lshl_add_u64 v[200:201], s[36:37], 0, v[0:1]
	s_add_u32 s76, s36, 0x40000
	ds_read_b128 v[162:165], v240 offset:16384
	ds_read_b128 v[166:169], v240 offset:17408
	ds_read_b128 v[170:173], v240 offset:18432
	ds_read_b128 v[174:177], v240 offset:19456
	ds_read_b128 v[178:181], v240 offset:20480
	ds_read_b128 v[182:185], v240 offset:21504
	ds_read_b128 v[186:189], v240 offset:22528
	ds_read_b128 v[190:193], v240 offset:23552
	global_load_lds_dwordx4 v[200:201], off
	v_lshl_add_u64 v[214:215], s[36:37], 0, v[208:209]
	s_mov_b32 m0, s52
	s_addc_u32 s77, s37, 0
	global_load_lds_dwordx4 v[214:215], off
	v_lshl_add_u64 v[216:217], s[76:77], 0, v[0:1]
	s_mov_b32 m0, s54
	v_lshl_add_u64 v[218:219], s[38:39], 0, v[206:207]
	global_load_lds_dwordx4 v[216:217], off
	v_lshl_add_u64 v[216:217], s[76:77], 0, v[208:209]
	s_mov_b32 m0, s55
	s_nop 0
	global_load_lds_dwordx4 v[216:217], off
	v_lshl_add_u64 v[216:217], s[38:39], 0, v[204:205]
	s_mov_b32 m0, s56
	s_nop 0
	global_load_lds_dwordx4 v[216:217], off
	s_mov_b32 m0, s57
	s_nop 0
	global_load_lds_dwordx4 v[218:219], off
	s_waitcnt vmcnt(8)
	s_waitcnt lgkmcnt(0)
	s_barrier
	s_setprio 1
	s_waitcnt lgkmcnt(0)
	v_mfma_f32_16x16x32_bf16 v[62:65], v[130:133], v[162:165], v[62:65]
	v_mfma_f32_16x16x32_bf16 v[58:61], v[138:141], v[162:165], v[58:61]
	v_mfma_f32_16x16x32_bf16 v[46:49], v[130:133], v[170:173], v[46:49]
	v_mfma_f32_16x16x32_bf16 v[42:45], v[138:141], v[170:173], v[42:45]
	v_mfma_f32_16x16x32_bf16 v[30:33], v[130:133], v[178:181], v[30:33]
	v_mfma_f32_16x16x32_bf16 v[26:29], v[138:141], v[178:181], v[26:29]
	v_mfma_f32_16x16x32_bf16 v[14:17], v[130:133], v[186:189], v[14:17]
	v_mfma_f32_16x16x32_bf16 v[10:13], v[138:141], v[186:189], v[10:13]
	v_mfma_f32_16x16x32_bf16 v[62:65], v[134:137], v[166:169], v[62:65]
	v_mfma_f32_16x16x32_bf16 v[58:61], v[142:145], v[166:169], v[58:61]
	v_mfma_f32_16x16x32_bf16 v[46:49], v[134:137], v[174:177], v[46:49]
	v_mfma_f32_16x16x32_bf16 v[42:45], v[142:145], v[174:177], v[42:45]
	v_mfma_f32_16x16x32_bf16 v[30:33], v[134:137], v[182:185], v[30:33]
	v_mfma_f32_16x16x32_bf16 v[26:29], v[142:145], v[182:185], v[26:29]
	v_mfma_f32_16x16x32_bf16 v[14:17], v[134:137], v[190:193], v[14:17]
	v_mfma_f32_16x16x32_bf16 v[10:13], v[142:145], v[190:193], v[10:13]
	v_mfma_f32_16x16x32_bf16 v[54:57], v[146:149], v[162:165], v[54:57]
	v_mfma_f32_16x16x32_bf16 v[50:53], v[154:157], v[162:165], v[50:53]
	v_mfma_f32_16x16x32_bf16 v[38:41], v[146:149], v[170:173], v[38:41]
	v_mfma_f32_16x16x32_bf16 v[34:37], v[154:157], v[170:173], v[34:37]
	v_mfma_f32_16x16x32_bf16 v[22:25], v[146:149], v[178:181], v[22:25]
	v_mfma_f32_16x16x32_bf16 v[18:21], v[154:157], v[178:181], v[18:21]
	v_mfma_f32_16x16x32_bf16 v[6:9], v[146:149], v[186:189], v[6:9]
	v_mfma_f32_16x16x32_bf16 v[2:5], v[154:157], v[186:189], v[2:5]
	v_mfma_f32_16x16x32_bf16 v[54:57], v[150:153], v[166:169], v[54:57]
	v_mfma_f32_16x16x32_bf16 v[50:53], v[158:161], v[166:169], v[50:53]
	v_mfma_f32_16x16x32_bf16 v[38:41], v[150:153], v[174:177], v[38:41]
	v_mfma_f32_16x16x32_bf16 v[34:37], v[158:161], v[174:177], v[34:37]
	v_mfma_f32_16x16x32_bf16 v[22:25], v[150:153], v[182:185], v[22:25]
	v_mfma_f32_16x16x32_bf16 v[18:21], v[158:161], v[182:185], v[18:21]
	v_mfma_f32_16x16x32_bf16 v[6:9], v[150:153], v[190:193], v[6:9]
	v_mfma_f32_16x16x32_bf16 v[2:5], v[158:161], v[190:193], v[2:5]
	s_setprio 0
	s_barrier
	v_add_u32_e32 v142, s62, v238
	v_add_u32_e32 v158, s67, v238
	ds_read_b128 v[130:133], v142
	ds_read_b128 v[134:137], v142 offset:1024
	ds_read_b128 v[138:141], v142 offset:2048
	ds_read_b128 v[142:145], v142 offset:3072
	ds_read_b128 v[146:149], v158
	ds_read_b128 v[150:153], v158 offset:1024
	ds_read_b128 v[154:157], v158 offset:2048
	ds_read_b128 v[158:161], v158 offset:3072
	s_add_u32 s38, s38, 0x40000
	s_addc_u32 s39, s39, 0
	s_mov_b32 m0, s58
	v_lshl_add_u64 v[220:221], s[38:39], 0, v[204:205]
	ds_read_b128 v[162:165], v240 offset:32768
	ds_read_b128 v[166:169], v240 offset:33792
	ds_read_b128 v[170:173], v240 offset:34816
	ds_read_b128 v[174:177], v240 offset:35840
	ds_read_b128 v[178:181], v240 offset:36864
	ds_read_b128 v[182:185], v240 offset:37888
	ds_read_b128 v[186:189], v240 offset:38912
	ds_read_b128 v[190:193], v240 offset:39936
	global_load_lds_dwordx4 v[220:221], off
	v_lshl_add_u64 v[220:221], s[38:39], 0, v[206:207]
	s_mov_b32 m0, s59
	s_nop 0
	global_load_lds_dwordx4 v[220:221], off
	s_waitcnt vmcnt(8)
	s_waitcnt lgkmcnt(0)
	s_barrier
	s_setprio 1
	s_waitcnt lgkmcnt(0)
	v_mfma_f32_16x16x32_bf16 v[126:129], v[130:133], v[162:165], v[126:129]
	v_mfma_f32_16x16x32_bf16 v[122:125], v[138:141], v[162:165], v[122:125]
	v_mfma_f32_16x16x32_bf16 v[110:113], v[130:133], v[170:173], v[110:113]
	v_mfma_f32_16x16x32_bf16 v[106:109], v[138:141], v[170:173], v[106:109]
	v_mfma_f32_16x16x32_bf16 v[94:97], v[130:133], v[178:181], v[94:97]
	v_mfma_f32_16x16x32_bf16 v[90:93], v[138:141], v[178:181], v[90:93]
	v_mfma_f32_16x16x32_bf16 v[78:81], v[130:133], v[186:189], v[78:81]
	v_mfma_f32_16x16x32_bf16 v[74:77], v[138:141], v[186:189], v[74:77]
	v_mfma_f32_16x16x32_bf16 v[126:129], v[134:137], v[166:169], v[126:129]
	v_mfma_f32_16x16x32_bf16 v[122:125], v[142:145], v[166:169], v[122:125]
	v_mfma_f32_16x16x32_bf16 v[110:113], v[134:137], v[174:177], v[110:113]
	v_mfma_f32_16x16x32_bf16 v[106:109], v[142:145], v[174:177], v[106:109]
	v_mfma_f32_16x16x32_bf16 v[94:97], v[134:137], v[182:185], v[94:97]
	v_mfma_f32_16x16x32_bf16 v[90:93], v[142:145], v[182:185], v[90:93]
	v_mfma_f32_16x16x32_bf16 v[78:81], v[134:137], v[190:193], v[78:81]
	v_mfma_f32_16x16x32_bf16 v[74:77], v[142:145], v[190:193], v[74:77]
	v_mfma_f32_16x16x32_bf16 v[118:121], v[146:149], v[162:165], v[118:121]
	v_mfma_f32_16x16x32_bf16 v[114:117], v[154:157], v[162:165], v[114:117]
	v_mfma_f32_16x16x32_bf16 v[102:105], v[146:149], v[170:173], v[102:105]
	v_mfma_f32_16x16x32_bf16 v[98:101], v[154:157], v[170:173], v[98:101]
	v_mfma_f32_16x16x32_bf16 v[86:89], v[146:149], v[178:181], v[86:89]
	v_mfma_f32_16x16x32_bf16 v[82:85], v[154:157], v[178:181], v[82:85]
	v_mfma_f32_16x16x32_bf16 v[70:73], v[146:149], v[186:189], v[70:73]
	v_mfma_f32_16x16x32_bf16 v[66:69], v[154:157], v[186:189], v[66:69]
	v_mfma_f32_16x16x32_bf16 v[118:121], v[150:153], v[166:169], v[118:121]
	v_mfma_f32_16x16x32_bf16 v[114:117], v[158:161], v[166:169], v[114:117]
	v_mfma_f32_16x16x32_bf16 v[102:105], v[150:153], v[174:177], v[102:105]
	v_mfma_f32_16x16x32_bf16 v[98:101], v[158:161], v[174:177], v[98:101]
	v_mfma_f32_16x16x32_bf16 v[86:89], v[150:153], v[182:185], v[86:89]
	v_mfma_f32_16x16x32_bf16 v[82:85], v[158:161], v[182:185], v[82:85]
	v_mfma_f32_16x16x32_bf16 v[70:73], v[150:153], v[190:193], v[70:73]
	v_mfma_f32_16x16x32_bf16 v[66:69], v[158:161], v[190:193], v[66:69]
	s_setprio 0
	s_barrier
	s_mov_b32 m0, s63
	v_lshl_add_u64 v[200:201], v[200:201], 0, s[80:81]
	s_add_u32 s36, s36, 0x40080
	ds_read_b128 v[162:165], v240 offset:49152
	ds_read_b128 v[166:169], v240 offset:50176
	ds_read_b128 v[170:173], v240 offset:51200
	ds_read_b128 v[174:177], v240 offset:52224
	ds_read_b128 v[178:181], v240 offset:53248
	ds_read_b128 v[182:185], v240 offset:54272
	ds_read_b128 v[186:189], v240 offset:55296
	ds_read_b128 v[190:193], v240 offset:56320
	global_load_lds_dwordx4 v[200:201], off
	v_lshl_add_u64 v[200:201], v[214:215], 0, s[80:81]
	s_mov_b32 m0, s64
	s_addc_u32 s37, s37, 0
	global_load_lds_dwordx4 v[200:201], off
	v_lshl_add_u64 v[200:201], s[36:37], 0, v[0:1]
	s_mov_b32 m0, s68
	s_nop 0
	global_load_lds_dwordx4 v[200:201], off
	v_lshl_add_u64 v[200:201], s[36:37], 0, v[208:209]
	s_mov_b32 m0, s69
	s_nop 0
	global_load_lds_dwordx4 v[200:201], off
	v_lshl_add_u64 v[200:201], v[216:217], 0, s[80:81]
	s_mov_b32 m0, s65
	s_nop 0
	global_load_lds_dwordx4 v[200:201], off
	v_lshl_add_u64 v[200:201], v[218:219], 0, s[80:81]
	s_mov_b32 m0, s66
	s_nop 0
	global_load_lds_dwordx4 v[200:201], off
	s_waitcnt vmcnt(8)
	s_waitcnt lgkmcnt(0)
	s_barrier
	s_setprio 1
	s_waitcnt lgkmcnt(0)
	v_mfma_f32_16x16x32_bf16 v[62:65], v[130:133], v[162:165], v[62:65]
	v_mfma_f32_16x16x32_bf16 v[58:61], v[138:141], v[162:165], v[58:61]
	v_mfma_f32_16x16x32_bf16 v[46:49], v[130:133], v[170:173], v[46:49]
	v_mfma_f32_16x16x32_bf16 v[42:45], v[138:141], v[170:173], v[42:45]
	v_mfma_f32_16x16x32_bf16 v[30:33], v[130:133], v[178:181], v[30:33]
	v_mfma_f32_16x16x32_bf16 v[26:29], v[138:141], v[178:181], v[26:29]
	v_mfma_f32_16x16x32_bf16 v[14:17], v[130:133], v[186:189], v[14:17]
	v_mfma_f32_16x16x32_bf16 v[10:13], v[138:141], v[186:189], v[10:13]
	v_mfma_f32_16x16x32_bf16 v[62:65], v[134:137], v[166:169], v[62:65]
	v_mfma_f32_16x16x32_bf16 v[58:61], v[142:145], v[166:169], v[58:61]
	v_mfma_f32_16x16x32_bf16 v[46:49], v[134:137], v[174:177], v[46:49]
	v_mfma_f32_16x16x32_bf16 v[42:45], v[142:145], v[174:177], v[42:45]
	v_mfma_f32_16x16x32_bf16 v[30:33], v[134:137], v[182:185], v[30:33]
	v_mfma_f32_16x16x32_bf16 v[26:29], v[142:145], v[182:185], v[26:29]
	v_mfma_f32_16x16x32_bf16 v[14:17], v[134:137], v[190:193], v[14:17]
	v_mfma_f32_16x16x32_bf16 v[10:13], v[142:145], v[190:193], v[10:13]
	v_mfma_f32_16x16x32_bf16 v[54:57], v[146:149], v[162:165], v[54:57]
	v_mfma_f32_16x16x32_bf16 v[50:53], v[154:157], v[162:165], v[50:53]
	v_mfma_f32_16x16x32_bf16 v[38:41], v[146:149], v[170:173], v[38:41]
	v_mfma_f32_16x16x32_bf16 v[34:37], v[154:157], v[170:173], v[34:37]
	v_mfma_f32_16x16x32_bf16 v[22:25], v[146:149], v[178:181], v[22:25]
	v_mfma_f32_16x16x32_bf16 v[18:21], v[154:157], v[178:181], v[18:21]
	v_mfma_f32_16x16x32_bf16 v[6:9], v[146:149], v[186:189], v[6:9]
	v_mfma_f32_16x16x32_bf16 v[2:5], v[154:157], v[186:189], v[2:5]
	v_mfma_f32_16x16x32_bf16 v[54:57], v[150:153], v[166:169], v[54:57]
	v_mfma_f32_16x16x32_bf16 v[50:53], v[158:161], v[166:169], v[50:53]
	v_mfma_f32_16x16x32_bf16 v[38:41], v[150:153], v[174:177], v[38:41]
	v_mfma_f32_16x16x32_bf16 v[34:37], v[158:161], v[174:177], v[34:37]
	v_mfma_f32_16x16x32_bf16 v[22:25], v[150:153], v[182:185], v[22:25]
	v_mfma_f32_16x16x32_bf16 v[18:21], v[158:161], v[182:185], v[18:21]
	v_mfma_f32_16x16x32_bf16 v[6:9], v[150:153], v[190:193], v[6:9]
	v_mfma_f32_16x16x32_bf16 v[2:5], v[158:161], v[190:193], v[2:5]
	s_setprio 0
	s_barrier
	s_add_i32 s74, s74, 2
	s_add_u32 s34, s34, 0x100
	s_addc_u32 s35, s35, 0
	s_add_u32 s72, s72, 0x100
	s_addc_u32 s73, s73, 0
	s_cmp_gt_u32 s74, 13
	s_cbranch_scc0 .LBB0_1107
	s_and_b64 vcc, exec, s[18:19]
	s_cbranch_vccz .LBB0_1110
	s_barrier

.LBB0_1223:
	v_add_u32_e32 v156, s46, v160
	ds_read_b128 v[166:169], v156
	ds_read_b128 v[170:173], v156 offset:1024
	ds_read_b128 v[174:177], v156 offset:2048
	ds_read_b128 v[178:181], v156 offset:3072
	v_add_u32_e32 v156, s49, v160
	ds_read_b128 v[182:185], v156
	ds_read_b128 v[186:189], v156 offset:1024
	ds_read_b128 v[190:193], v156 offset:2048
	ds_read_b128 v[204:207], v156 offset:3072
	s_add_u32 s30, s28, 0xfffc0080
	s_addc_u32 s31, s29, -1
	s_cmp_eq_u32 s71, 12
	s_cselect_b32 s35, s21, s31
	s_cselect_b32 s34, s67, s30
	s_cselect_b32 s31, s19, s70
	s_cselect_b32 s30, s68, s69
	v_lshl_add_u64 v[156:157], s[28:29], 0, v[152:153]
	s_add_i32 m0, s52, 0xc000
	ds_read_b128 v[208:211], v164
	ds_read_b128 v[212:215], v164 offset:1024
	ds_read_b128 v[216:219], v164 offset:2048
	ds_read_b128 v[220:223], v164 offset:3072
	ds_read_b128 v[224:227], v164 offset:4096
	ds_read_b128 v[228:231], v164 offset:5120
	ds_read_b128 v[238:241], v164 offset:6144
	ds_read_b128 v[242:245], v164 offset:7168
	global_load_lds_dwordx4 v[156:157], off
	v_lshl_add_u64 v[156:157], s[28:29], 0, v[154:155]
	s_add_i32 m0, s52, 0xe000
	s_nop 0
	global_load_lds_dwordx4 v[156:157], off
	s_waitcnt vmcnt(8)
	s_waitcnt lgkmcnt(0)
	s_barrier
	s_setprio 1
	s_waitcnt lgkmcnt(0)
	v_mfma_f32_16x16x32_bf16 v[142:145], v[166:169], v[208:211], v[142:145]
	v_mfma_f32_16x16x32_bf16 v[138:141], v[174:177], v[208:211], v[138:141]
	v_mfma_f32_16x16x32_bf16 v[126:129], v[166:169], v[216:219], v[126:129]
	v_mfma_f32_16x16x32_bf16 v[122:125], v[174:177], v[216:219], v[122:125]
	v_mfma_f32_16x16x32_bf16 v[110:113], v[166:169], v[224:227], v[110:113]
	v_mfma_f32_16x16x32_bf16 v[106:109], v[174:177], v[224:227], v[106:109]
	v_mfma_f32_16x16x32_bf16 v[94:97], v[166:169], v[238:241], v[94:97]
	v_mfma_f32_16x16x32_bf16 v[90:93], v[174:177], v[238:241], v[90:93]
	v_mfma_f32_16x16x32_bf16 v[142:145], v[170:173], v[212:215], v[142:145]
	v_mfma_f32_16x16x32_bf16 v[138:141], v[178:181], v[212:215], v[138:141]
	v_mfma_f32_16x16x32_bf16 v[126:129], v[170:173], v[220:223], v[126:129]
	v_mfma_f32_16x16x32_bf16 v[122:125], v[178:181], v[220:223], v[122:125]
	v_mfma_f32_16x16x32_bf16 v[110:113], v[170:173], v[228:231], v[110:113]
	v_mfma_f32_16x16x32_bf16 v[106:109], v[178:181], v[228:231], v[106:109]
	v_mfma_f32_16x16x32_bf16 v[94:97], v[170:173], v[242:245], v[94:97]
	v_mfma_f32_16x16x32_bf16 v[90:93], v[178:181], v[242:245], v[90:93]
	v_mfma_f32_16x16x32_bf16 v[134:137], v[182:185], v[208:211], v[134:137]
	v_mfma_f32_16x16x32_bf16 v[130:133], v[190:193], v[208:211], v[130:133]
	v_mfma_f32_16x16x32_bf16 v[118:121], v[182:185], v[216:219], v[118:121]
	v_mfma_f32_16x16x32_bf16 v[114:117], v[190:193], v[216:219], v[114:117]
	v_mfma_f32_16x16x32_bf16 v[102:105], v[182:185], v[224:227], v[102:105]
	v_mfma_f32_16x16x32_bf16 v[98:101], v[190:193], v[224:227], v[98:101]
	v_mfma_f32_16x16x32_bf16 v[86:89], v[182:185], v[238:241], v[86:89]
	v_mfma_f32_16x16x32_bf16 v[82:85], v[190:193], v[238:241], v[82:85]
	v_mfma_f32_16x16x32_bf16 v[134:137], v[186:189], v[212:215], v[134:137]
	v_mfma_f32_16x16x32_bf16 v[130:133], v[204:207], v[212:215], v[130:133]
	v_mfma_f32_16x16x32_bf16 v[118:121], v[186:189], v[220:223], v[118:121]
	v_mfma_f32_16x16x32_bf16 v[114:117], v[204:207], v[220:223], v[114:117]
	v_mfma_f32_16x16x32_bf16 v[102:105], v[186:189], v[228:231], v[102:105]
	v_mfma_f32_16x16x32_bf16 v[98:101], v[204:207], v[228:231], v[98:101]
	v_mfma_f32_16x16x32_bf16 v[86:89], v[186:189], v[242:245], v[86:89]
	v_mfma_f32_16x16x32_bf16 v[82:85], v[204:207], v[242:245], v[82:85]
	s_setprio 0
	s_barrier
	s_mov_b32 m0, s47
	v_lshl_add_u64 v[156:157], s[30:31], 0, v[0:1]
	s_add_u32 s72, s30, 0x40000
	ds_read_b128 v[208:211], v164 offset:16384
	ds_read_b128 v[212:215], v164 offset:17408
	ds_read_b128 v[216:219], v164 offset:18432
	ds_read_b128 v[220:223], v164 offset:19456
	ds_read_b128 v[224:227], v164 offset:20480
	ds_read_b128 v[228:231], v164 offset:21504
	ds_read_b128 v[238:241], v164 offset:22528
	ds_read_b128 v[242:245], v164 offset:23552
	global_load_lds_dwordx4 v[156:157], off
	v_lshl_add_u64 v[200:201], s[30:31], 0, v[150:151]
	s_mov_b32 m0, s48
	s_addc_u32 s73, s31, 0
	global_load_lds_dwordx4 v[200:201], off
	v_lshl_add_u64 v[232:233], s[72:73], 0, v[0:1]
	s_mov_b32 m0, s50
	v_lshl_add_u64 v[246:247], s[34:35], 0, v[148:149]
	global_load_lds_dwordx4 v[232:233], off
	v_lshl_add_u64 v[232:233], s[72:73], 0, v[150:151]
	s_mov_b32 m0, s51
	s_nop 0
	global_load_lds_dwordx4 v[232:233], off
	v_lshl_add_u64 v[232:233], s[34:35], 0, v[146:147]
	s_mov_b32 m0, s52
	s_nop 0
	global_load_lds_dwordx4 v[232:233], off
	s_mov_b32 m0, s53
	s_nop 0
	global_load_lds_dwordx4 v[246:247], off
	s_waitcnt vmcnt(8)
	s_waitcnt lgkmcnt(0)
	s_barrier
	s_setprio 1
	s_waitcnt lgkmcnt(0)
	v_mfma_f32_16x16x32_bf16 v[78:81], v[166:169], v[208:211], v[78:81]
	v_mfma_f32_16x16x32_bf16 v[74:77], v[174:177], v[208:211], v[74:77]
	v_mfma_f32_16x16x32_bf16 v[62:65], v[166:169], v[216:219], v[62:65]
	v_mfma_f32_16x16x32_bf16 v[58:61], v[174:177], v[216:219], v[58:61]
	v_mfma_f32_16x16x32_bf16 v[46:49], v[166:169], v[224:227], v[46:49]
	v_mfma_f32_16x16x32_bf16 v[42:45], v[174:177], v[224:227], v[42:45]
	v_mfma_f32_16x16x32_bf16 v[30:33], v[166:169], v[238:241], v[30:33]
	v_mfma_f32_16x16x32_bf16 v[26:29], v[174:177], v[238:241], v[26:29]
	v_mfma_f32_16x16x32_bf16 v[78:81], v[170:173], v[212:215], v[78:81]
	v_mfma_f32_16x16x32_bf16 v[74:77], v[178:181], v[212:215], v[74:77]
	v_mfma_f32_16x16x32_bf16 v[62:65], v[170:173], v[220:223], v[62:65]
	v_mfma_f32_16x16x32_bf16 v[58:61], v[178:181], v[220:223], v[58:61]
	v_mfma_f32_16x16x32_bf16 v[46:49], v[170:173], v[228:231], v[46:49]
	v_mfma_f32_16x16x32_bf16 v[42:45], v[178:181], v[228:231], v[42:45]
	v_mfma_f32_16x16x32_bf16 v[30:33], v[170:173], v[242:245], v[30:33]
	v_mfma_f32_16x16x32_bf16 v[26:29], v[178:181], v[242:245], v[26:29]
	v_mfma_f32_16x16x32_bf16 v[70:73], v[182:185], v[208:211], v[70:73]
	v_mfma_f32_16x16x32_bf16 v[66:69], v[190:193], v[208:211], v[66:69]
	v_mfma_f32_16x16x32_bf16 v[54:57], v[182:185], v[216:219], v[54:57]
	v_mfma_f32_16x16x32_bf16 v[50:53], v[190:193], v[216:219], v[50:53]
	v_mfma_f32_16x16x32_bf16 v[38:41], v[182:185], v[224:227], v[38:41]
	v_mfma_f32_16x16x32_bf16 v[34:37], v[190:193], v[224:227], v[34:37]
	v_mfma_f32_16x16x32_bf16 v[22:25], v[182:185], v[238:241], v[22:25]
	v_mfma_f32_16x16x32_bf16 v[18:21], v[190:193], v[238:241], v[18:21]
	v_mfma_f32_16x16x32_bf16 v[70:73], v[186:189], v[212:215], v[70:73]
	v_mfma_f32_16x16x32_bf16 v[66:69], v[204:207], v[212:215], v[66:69]
	v_mfma_f32_16x16x32_bf16 v[54:57], v[186:189], v[220:223], v[54:57]
	v_mfma_f32_16x16x32_bf16 v[50:53], v[204:207], v[220:223], v[50:53]
	v_mfma_f32_16x16x32_bf16 v[38:41], v[186:189], v[228:231], v[38:41]
	v_mfma_f32_16x16x32_bf16 v[34:37], v[204:207], v[228:231], v[34:37]
	v_mfma_f32_16x16x32_bf16 v[22:25], v[186:189], v[242:245], v[22:25]
	v_mfma_f32_16x16x32_bf16 v[18:21], v[204:207], v[242:245], v[18:21]
	s_setprio 0
	s_barrier
	v_add_u32_e32 v165, s56, v160
	ds_read_b128 v[166:169], v165
	ds_read_b128 v[170:173], v165 offset:1024
	ds_read_b128 v[174:177], v165 offset:2048
	ds_read_b128 v[178:181], v165 offset:3072
	v_add_u32_e32 v165, s61, v160
	ds_read_b128 v[182:185], v165
	ds_read_b128 v[186:189], v165 offset:1024
	ds_read_b128 v[190:193], v165 offset:2048
	ds_read_b128 v[204:207], v165 offset:3072
	s_add_u32 s34, s34, 0x40000
	s_addc_u32 s35, s35, 0
	s_mov_b32 m0, s54
	v_lshl_add_u64 v[248:249], s[34:35], 0, v[146:147]
	ds_read_b128 v[208:211], v164 offset:32768
	ds_read_b128 v[212:215], v164 offset:33792
	ds_read_b128 v[216:219], v164 offset:34816
	ds_read_b128 v[220:223], v164 offset:35840
	ds_read_b128 v[224:227], v164 offset:36864
	ds_read_b128 v[228:231], v164 offset:37888
	ds_read_b128 v[238:241], v164 offset:38912
	ds_read_b128 v[242:245], v164 offset:39936
	global_load_lds_dwordx4 v[248:249], off
	v_lshl_add_u64 v[248:249], s[34:35], 0, v[148:149]
	s_mov_b32 m0, s55
	s_nop 0
	global_load_lds_dwordx4 v[248:249], off
	s_waitcnt vmcnt(8)
	s_waitcnt lgkmcnt(0)
	s_barrier
	s_setprio 1
	s_waitcnt lgkmcnt(0)
	v_mfma_f32_16x16x32_bf16 v[142:145], v[166:169], v[208:211], v[142:145]
	v_mfma_f32_16x16x32_bf16 v[138:141], v[174:177], v[208:211], v[138:141]
	v_mfma_f32_16x16x32_bf16 v[126:129], v[166:169], v[216:219], v[126:129]
	v_mfma_f32_16x16x32_bf16 v[122:125], v[174:177], v[216:219], v[122:125]
	v_mfma_f32_16x16x32_bf16 v[110:113], v[166:169], v[224:227], v[110:113]
	v_mfma_f32_16x16x32_bf16 v[106:109], v[174:177], v[224:227], v[106:109]
	v_mfma_f32_16x16x32_bf16 v[94:97], v[166:169], v[238:241], v[94:97]
	v_mfma_f32_16x16x32_bf16 v[90:93], v[174:177], v[238:241], v[90:93]
	v_mfma_f32_16x16x32_bf16 v[142:145], v[170:173], v[212:215], v[142:145]
	v_mfma_f32_16x16x32_bf16 v[138:141], v[178:181], v[212:215], v[138:141]
	v_mfma_f32_16x16x32_bf16 v[126:129], v[170:173], v[220:223], v[126:129]
	v_mfma_f32_16x16x32_bf16 v[122:125], v[178:181], v[220:223], v[122:125]
	v_mfma_f32_16x16x32_bf16 v[110:113], v[170:173], v[228:231], v[110:113]
	v_mfma_f32_16x16x32_bf16 v[106:109], v[178:181], v[228:231], v[106:109]
	v_mfma_f32_16x16x32_bf16 v[94:97], v[170:173], v[242:245], v[94:97]
	v_mfma_f32_16x16x32_bf16 v[90:93], v[178:181], v[242:245], v[90:93]
	v_mfma_f32_16x16x32_bf16 v[134:137], v[182:185], v[208:211], v[134:137]
	v_mfma_f32_16x16x32_bf16 v[130:133], v[190:193], v[208:211], v[130:133]
	v_mfma_f32_16x16x32_bf16 v[118:121], v[182:185], v[216:219], v[118:121]
	v_mfma_f32_16x16x32_bf16 v[114:117], v[190:193], v[216:219], v[114:117]
	v_mfma_f32_16x16x32_bf16 v[102:105], v[182:185], v[224:227], v[102:105]
	v_mfma_f32_16x16x32_bf16 v[98:101], v[190:193], v[224:227], v[98:101]
	v_mfma_f32_16x16x32_bf16 v[86:89], v[182:185], v[238:241], v[86:89]
	v_mfma_f32_16x16x32_bf16 v[82:85], v[190:193], v[238:241], v[82:85]
	v_mfma_f32_16x16x32_bf16 v[134:137], v[186:189], v[212:215], v[134:137]
	v_mfma_f32_16x16x32_bf16 v[130:133], v[204:207], v[212:215], v[130:133]
	v_mfma_f32_16x16x32_bf16 v[118:121], v[186:189], v[220:223], v[118:121]
	v_mfma_f32_16x16x32_bf16 v[114:117], v[204:207], v[220:223], v[114:117]
	v_mfma_f32_16x16x32_bf16 v[102:105], v[186:189], v[228:231], v[102:105]
	v_mfma_f32_16x16x32_bf16 v[98:101], v[204:207], v[228:231], v[98:101]
	v_mfma_f32_16x16x32_bf16 v[86:89], v[186:189], v[242:245], v[86:89]
	v_mfma_f32_16x16x32_bf16 v[82:85], v[204:207], v[242:245], v[82:85]
	s_setprio 0
	s_barrier
	s_mov_b32 m0, s57
	v_lshl_add_u64 v[156:157], v[156:157], 0, s[80:81]
	s_add_u32 s30, s30, 0x40080
	ds_read_b128 v[208:211], v164 offset:49152
	ds_read_b128 v[212:215], v164 offset:50176
	ds_read_b128 v[216:219], v164 offset:51200
	ds_read_b128 v[220:223], v164 offset:52224
	ds_read_b128 v[224:227], v164 offset:53248
	ds_read_b128 v[228:231], v164 offset:54272
	ds_read_b128 v[238:241], v164 offset:55296
	ds_read_b128 v[242:245], v164 offset:56320
	global_load_lds_dwordx4 v[156:157], off
	v_lshl_add_u64 v[156:157], v[200:201], 0, s[80:81]
	s_mov_b32 m0, s58
	s_addc_u32 s31, s31, 0
	global_load_lds_dwordx4 v[156:157], off
	v_lshl_add_u64 v[156:157], s[30:31], 0, v[0:1]
	s_mov_b32 m0, s62
	s_nop 0
	global_load_lds_dwordx4 v[156:157], off
	v_lshl_add_u64 v[156:157], s[30:31], 0, v[150:151]
	s_mov_b32 m0, s63
	s_nop 0
	global_load_lds_dwordx4 v[156:157], off
	v_lshl_add_u64 v[156:157], v[232:233], 0, s[80:81]
	s_mov_b32 m0, s59
	s_nop 0
	global_load_lds_dwordx4 v[156:157], off
	v_lshl_add_u64 v[156:157], v[246:247], 0, s[80:81]
	s_mov_b32 m0, s60
	s_nop 0
	global_load_lds_dwordx4 v[156:157], off
	s_waitcnt vmcnt(8)
	s_waitcnt lgkmcnt(0)
	s_barrier
	s_setprio 1
	s_waitcnt lgkmcnt(0)
	v_mfma_f32_16x16x32_bf16 v[78:81], v[166:169], v[208:211], v[78:81]
	v_mfma_f32_16x16x32_bf16 v[74:77], v[174:177], v[208:211], v[74:77]
	v_mfma_f32_16x16x32_bf16 v[62:65], v[166:169], v[216:219], v[62:65]
	v_mfma_f32_16x16x32_bf16 v[58:61], v[174:177], v[216:219], v[58:61]
	v_mfma_f32_16x16x32_bf16 v[46:49], v[166:169], v[224:227], v[46:49]
	v_mfma_f32_16x16x32_bf16 v[42:45], v[174:177], v[224:227], v[42:45]
	v_mfma_f32_16x16x32_bf16 v[30:33], v[166:169], v[238:241], v[30:33]
	v_mfma_f32_16x16x32_bf16 v[26:29], v[174:177], v[238:241], v[26:29]
	v_mfma_f32_16x16x32_bf16 v[78:81], v[170:173], v[212:215], v[78:81]
	v_mfma_f32_16x16x32_bf16 v[74:77], v[178:181], v[212:215], v[74:77]
	v_mfma_f32_16x16x32_bf16 v[62:65], v[170:173], v[220:223], v[62:65]
	v_mfma_f32_16x16x32_bf16 v[58:61], v[178:181], v[220:223], v[58:61]
	v_mfma_f32_16x16x32_bf16 v[46:49], v[170:173], v[228:231], v[46:49]
	v_mfma_f32_16x16x32_bf16 v[42:45], v[178:181], v[228:231], v[42:45]
	v_mfma_f32_16x16x32_bf16 v[30:33], v[170:173], v[242:245], v[30:33]
	v_mfma_f32_16x16x32_bf16 v[26:29], v[178:181], v[242:245], v[26:29]
	v_mfma_f32_16x16x32_bf16 v[70:73], v[182:185], v[208:211], v[70:73]
	v_mfma_f32_16x16x32_bf16 v[66:69], v[190:193], v[208:211], v[66:69]
	v_mfma_f32_16x16x32_bf16 v[54:57], v[182:185], v[216:219], v[54:57]
	v_mfma_f32_16x16x32_bf16 v[50:53], v[190:193], v[216:219], v[50:53]
	v_mfma_f32_16x16x32_bf16 v[38:41], v[182:185], v[224:227], v[38:41]
	v_mfma_f32_16x16x32_bf16 v[34:37], v[190:193], v[224:227], v[34:37]
	v_mfma_f32_16x16x32_bf16 v[22:25], v[182:185], v[238:241], v[22:25]
	v_mfma_f32_16x16x32_bf16 v[18:21], v[190:193], v[238:241], v[18:21]
	v_mfma_f32_16x16x32_bf16 v[70:73], v[186:189], v[212:215], v[70:73]
	v_mfma_f32_16x16x32_bf16 v[66:69], v[204:207], v[212:215], v[66:69]
	v_mfma_f32_16x16x32_bf16 v[54:57], v[186:189], v[220:223], v[54:57]
	v_mfma_f32_16x16x32_bf16 v[50:53], v[204:207], v[220:223], v[50:53]
	v_mfma_f32_16x16x32_bf16 v[38:41], v[186:189], v[228:231], v[38:41]
	v_mfma_f32_16x16x32_bf16 v[34:37], v[204:207], v[228:231], v[34:37]
	v_mfma_f32_16x16x32_bf16 v[22:25], v[186:189], v[242:245], v[22:25]
	v_mfma_f32_16x16x32_bf16 v[18:21], v[204:207], v[242:245], v[18:21]
	s_setprio 0
	s_barrier
	s_add_i32 s71, s71, 2
	s_add_u32 s28, s28, 0x100
	s_addc_u32 s29, s29, 0
	s_add_u32 s69, s69, 0x100
	s_addc_u32 s70, s70, 0
	s_cmp_gt_u32 s71, 13
	s_cbranch_scc0 .LBB0_1223
	s_and_b64 vcc, exec, s[16:17]
	s_cbranch_vccz .LBB0_1226
	s_barrier

.LBB0_1325:
	v_add_u32_e32 v142, s44, v183
	v_add_u32_e32 v168, s47, v183
	ds_read_b128 v[130:133], v142
	ds_read_b128 v[134:137], v142 offset:1024
	ds_read_b128 v[138:141], v142 offset:2048
	ds_read_b128 v[142:145], v142 offset:3072
	ds_read_b128 v[146:149], v168
	ds_read_b128 v[150:153], v168 offset:1024
	ds_read_b128 v[164:167], v168 offset:2048
	ds_read_b128 v[168:171], v168 offset:3072
	s_add_u32 s28, s26, 0xfff00080
	s_addc_u32 s29, s27, -1
	s_cmp_eq_u32 s68, 60
	s_cselect_b32 s31, s17, s29
	s_cselect_b32 s30, s23, s28
	s_cselect_b32 s29, s15, s67
	s_cselect_b32 s28, s25, s66
	v_lshl_add_u64 v[180:181], s[26:27], 0, v[160:161]
	s_add_i32 m0, s50, 0xc000
	ds_read_b128 v[172:175], v185
	ds_read_b128 v[176:179], v185 offset:1024
	ds_read_b128 v[186:189], v185 offset:2048
	ds_read_b128 v[190:193], v185 offset:3072
	ds_read_b128 v[204:207], v185 offset:4096
	ds_read_b128 v[208:211], v185 offset:5120
	ds_read_b128 v[212:215], v185 offset:6144
	ds_read_b128 v[216:219], v185 offset:7168
	global_load_lds_dwordx4 v[180:181], off
	v_lshl_add_u64 v[180:181], s[26:27], 0, v[162:163]
	s_add_i32 m0, s50, 0xe000
	s_nop 0
	global_load_lds_dwordx4 v[180:181], off
	s_waitcnt vmcnt(8)
	s_waitcnt lgkmcnt(0)
	s_barrier
	s_setprio 1
	s_waitcnt lgkmcnt(0)
	v_mfma_f32_16x16x32_bf16 v[126:129], v[130:133], v[172:175], v[126:129]
	v_mfma_f32_16x16x32_bf16 v[122:125], v[138:141], v[172:175], v[122:125]
	v_mfma_f32_16x16x32_bf16 v[110:113], v[130:133], v[186:189], v[110:113]
	v_mfma_f32_16x16x32_bf16 v[106:109], v[138:141], v[186:189], v[106:109]
	v_mfma_f32_16x16x32_bf16 v[94:97], v[130:133], v[204:207], v[94:97]
	v_mfma_f32_16x16x32_bf16 v[90:93], v[138:141], v[204:207], v[90:93]
	v_mfma_f32_16x16x32_bf16 v[78:81], v[130:133], v[212:215], v[78:81]
	v_mfma_f32_16x16x32_bf16 v[74:77], v[138:141], v[212:215], v[74:77]
	v_mfma_f32_16x16x32_bf16 v[126:129], v[134:137], v[176:179], v[126:129]
	v_mfma_f32_16x16x32_bf16 v[122:125], v[142:145], v[176:179], v[122:125]
	v_mfma_f32_16x16x32_bf16 v[110:113], v[134:137], v[190:193], v[110:113]
	v_mfma_f32_16x16x32_bf16 v[106:109], v[142:145], v[190:193], v[106:109]
	v_mfma_f32_16x16x32_bf16 v[94:97], v[134:137], v[208:211], v[94:97]
	v_mfma_f32_16x16x32_bf16 v[90:93], v[142:145], v[208:211], v[90:93]
	v_mfma_f32_16x16x32_bf16 v[78:81], v[134:137], v[216:219], v[78:81]
	v_mfma_f32_16x16x32_bf16 v[74:77], v[142:145], v[216:219], v[74:77]
	v_mfma_f32_16x16x32_bf16 v[118:121], v[146:149], v[172:175], v[118:121]
	v_mfma_f32_16x16x32_bf16 v[114:117], v[164:167], v[172:175], v[114:117]
	v_mfma_f32_16x16x32_bf16 v[102:105], v[146:149], v[186:189], v[102:105]
	v_mfma_f32_16x16x32_bf16 v[98:101], v[164:167], v[186:189], v[98:101]
	v_mfma_f32_16x16x32_bf16 v[86:89], v[146:149], v[204:207], v[86:89]
	v_mfma_f32_16x16x32_bf16 v[82:85], v[164:167], v[204:207], v[82:85]
	v_mfma_f32_16x16x32_bf16 v[70:73], v[146:149], v[212:215], v[70:73]
	v_mfma_f32_16x16x32_bf16 v[66:69], v[164:167], v[212:215], v[66:69]
	v_mfma_f32_16x16x32_bf16 v[118:121], v[150:153], v[176:179], v[118:121]
	v_mfma_f32_16x16x32_bf16 v[114:117], v[168:171], v[176:179], v[114:117]
	v_mfma_f32_16x16x32_bf16 v[102:105], v[150:153], v[190:193], v[102:105]
	v_mfma_f32_16x16x32_bf16 v[98:101], v[168:171], v[190:193], v[98:101]
	v_mfma_f32_16x16x32_bf16 v[86:89], v[150:153], v[208:211], v[86:89]
	v_mfma_f32_16x16x32_bf16 v[82:85], v[168:171], v[208:211], v[82:85]
	v_mfma_f32_16x16x32_bf16 v[70:73], v[150:153], v[216:219], v[70:73]
	v_mfma_f32_16x16x32_bf16 v[66:69], v[168:171], v[216:219], v[66:69]
	s_setprio 0
	s_barrier
	s_mov_b32 m0, s45
	v_lshl_add_u64 v[180:181], s[28:29], 0, v[0:1]
	s_add_u32 s70, s28, 0x100000
	ds_read_b128 v[172:175], v185 offset:16384
	ds_read_b128 v[176:179], v185 offset:17408
	ds_read_b128 v[186:189], v185 offset:18432
	ds_read_b128 v[190:193], v185 offset:19456
	ds_read_b128 v[204:207], v185 offset:20480
	ds_read_b128 v[208:211], v185 offset:21504
	ds_read_b128 v[212:215], v185 offset:22528
	ds_read_b128 v[216:219], v185 offset:23552
	global_load_lds_dwordx4 v[180:181], off
	v_lshl_add_u64 v[200:201], s[28:29], 0, v[158:159]
	s_mov_b32 m0, s46
	s_addc_u32 s71, s29, 0
	global_load_lds_dwordx4 v[200:201], off
	v_lshl_add_u64 v[220:221], s[70:71], 0, v[0:1]
	s_mov_b32 m0, s48
	v_lshl_add_u64 v[222:223], s[30:31], 0, v[156:157]
	global_load_lds_dwordx4 v[220:221], off
	v_lshl_add_u64 v[220:221], s[70:71], 0, v[158:159]
	s_mov_b32 m0, s49
	s_nop 0
	global_load_lds_dwordx4 v[220:221], off
	v_lshl_add_u64 v[220:221], s[30:31], 0, v[154:155]
	s_mov_b32 m0, s50
	s_nop 0
	global_load_lds_dwordx4 v[220:221], off
	s_mov_b32 m0, s51
	s_nop 0
	global_load_lds_dwordx4 v[222:223], off
	s_waitcnt vmcnt(8)
	s_waitcnt lgkmcnt(0)
	s_barrier
	s_setprio 1
	s_waitcnt lgkmcnt(0)
	v_mfma_f32_16x16x32_bf16 v[62:65], v[130:133], v[172:175], v[62:65]
	v_mfma_f32_16x16x32_bf16 v[58:61], v[138:141], v[172:175], v[58:61]
	v_mfma_f32_16x16x32_bf16 v[46:49], v[130:133], v[186:189], v[46:49]
	v_mfma_f32_16x16x32_bf16 v[42:45], v[138:141], v[186:189], v[42:45]
	v_mfma_f32_16x16x32_bf16 v[30:33], v[130:133], v[204:207], v[30:33]
	v_mfma_f32_16x16x32_bf16 v[26:29], v[138:141], v[204:207], v[26:29]
	v_mfma_f32_16x16x32_bf16 v[14:17], v[130:133], v[212:215], v[14:17]
	v_mfma_f32_16x16x32_bf16 v[10:13], v[138:141], v[212:215], v[10:13]
	v_mfma_f32_16x16x32_bf16 v[62:65], v[134:137], v[176:179], v[62:65]
	v_mfma_f32_16x16x32_bf16 v[58:61], v[142:145], v[176:179], v[58:61]
	v_mfma_f32_16x16x32_bf16 v[46:49], v[134:137], v[190:193], v[46:49]
	v_mfma_f32_16x16x32_bf16 v[42:45], v[142:145], v[190:193], v[42:45]
	v_mfma_f32_16x16x32_bf16 v[30:33], v[134:137], v[208:211], v[30:33]
	v_mfma_f32_16x16x32_bf16 v[26:29], v[142:145], v[208:211], v[26:29]
	v_mfma_f32_16x16x32_bf16 v[14:17], v[134:137], v[216:219], v[14:17]
	v_mfma_f32_16x16x32_bf16 v[10:13], v[142:145], v[216:219], v[10:13]
	v_mfma_f32_16x16x32_bf16 v[54:57], v[146:149], v[172:175], v[54:57]
	v_mfma_f32_16x16x32_bf16 v[50:53], v[164:167], v[172:175], v[50:53]
	v_mfma_f32_16x16x32_bf16 v[38:41], v[146:149], v[186:189], v[38:41]
	v_mfma_f32_16x16x32_bf16 v[34:37], v[164:167], v[186:189], v[34:37]
	v_mfma_f32_16x16x32_bf16 v[22:25], v[146:149], v[204:207], v[22:25]
	v_mfma_f32_16x16x32_bf16 v[18:21], v[164:167], v[204:207], v[18:21]
	v_mfma_f32_16x16x32_bf16 v[6:9], v[146:149], v[212:215], v[6:9]
	v_mfma_f32_16x16x32_bf16 v[2:5], v[164:167], v[212:215], v[2:5]
	v_mfma_f32_16x16x32_bf16 v[54:57], v[150:153], v[176:179], v[54:57]
	v_mfma_f32_16x16x32_bf16 v[50:53], v[168:171], v[176:179], v[50:53]
	v_mfma_f32_16x16x32_bf16 v[38:41], v[150:153], v[190:193], v[38:41]
	v_mfma_f32_16x16x32_bf16 v[34:37], v[168:171], v[190:193], v[34:37]
	v_mfma_f32_16x16x32_bf16 v[22:25], v[150:153], v[208:211], v[22:25]
	v_mfma_f32_16x16x32_bf16 v[18:21], v[168:171], v[208:211], v[18:21]
	v_mfma_f32_16x16x32_bf16 v[6:9], v[150:153], v[216:219], v[6:9]
	v_mfma_f32_16x16x32_bf16 v[2:5], v[168:171], v[216:219], v[2:5]
	s_setprio 0
	s_barrier
	v_add_u32_e32 v142, s55, v183
	v_add_u32_e32 v168, s60, v183
	ds_read_b128 v[130:133], v142
	ds_read_b128 v[134:137], v142 offset:1024
	ds_read_b128 v[138:141], v142 offset:2048
	ds_read_b128 v[142:145], v142 offset:3072
	ds_read_b128 v[146:149], v168
	ds_read_b128 v[150:153], v168 offset:1024
	ds_read_b128 v[164:167], v168 offset:2048
	ds_read_b128 v[168:171], v168 offset:3072
	s_add_u32 s30, s30, 0x100000
	s_addc_u32 s31, s31, 0
	s_mov_b32 m0, s52
	v_lshl_add_u64 v[224:225], s[30:31], 0, v[154:155]
	ds_read_b128 v[172:175], v185 offset:32768
	ds_read_b128 v[176:179], v185 offset:33792
	ds_read_b128 v[186:189], v185 offset:34816
	ds_read_b128 v[190:193], v185 offset:35840
	ds_read_b128 v[204:207], v185 offset:36864
	ds_read_b128 v[208:211], v185 offset:37888
	ds_read_b128 v[212:215], v185 offset:38912
	ds_read_b128 v[216:219], v185 offset:39936
	global_load_lds_dwordx4 v[224:225], off
	v_lshl_add_u64 v[224:225], s[30:31], 0, v[156:157]
	s_mov_b32 m0, s53
	s_nop 0
	global_load_lds_dwordx4 v[224:225], off
	s_waitcnt vmcnt(8)
	s_waitcnt lgkmcnt(0)
	s_barrier
	s_setprio 1
	s_waitcnt lgkmcnt(0)
	v_mfma_f32_16x16x32_bf16 v[126:129], v[130:133], v[172:175], v[126:129]
	v_mfma_f32_16x16x32_bf16 v[122:125], v[138:141], v[172:175], v[122:125]
	v_mfma_f32_16x16x32_bf16 v[110:113], v[130:133], v[186:189], v[110:113]
	v_mfma_f32_16x16x32_bf16 v[106:109], v[138:141], v[186:189], v[106:109]
	v_mfma_f32_16x16x32_bf16 v[94:97], v[130:133], v[204:207], v[94:97]
	v_mfma_f32_16x16x32_bf16 v[90:93], v[138:141], v[204:207], v[90:93]
	v_mfma_f32_16x16x32_bf16 v[78:81], v[130:133], v[212:215], v[78:81]
	v_mfma_f32_16x16x32_bf16 v[74:77], v[138:141], v[212:215], v[74:77]
	v_mfma_f32_16x16x32_bf16 v[126:129], v[134:137], v[176:179], v[126:129]
	v_mfma_f32_16x16x32_bf16 v[122:125], v[142:145], v[176:179], v[122:125]
	v_mfma_f32_16x16x32_bf16 v[110:113], v[134:137], v[190:193], v[110:113]
	v_mfma_f32_16x16x32_bf16 v[106:109], v[142:145], v[190:193], v[106:109]
	v_mfma_f32_16x16x32_bf16 v[94:97], v[134:137], v[208:211], v[94:97]
	v_mfma_f32_16x16x32_bf16 v[90:93], v[142:145], v[208:211], v[90:93]
	v_mfma_f32_16x16x32_bf16 v[78:81], v[134:137], v[216:219], v[78:81]
	v_mfma_f32_16x16x32_bf16 v[74:77], v[142:145], v[216:219], v[74:77]
	v_mfma_f32_16x16x32_bf16 v[118:121], v[146:149], v[172:175], v[118:121]
	v_mfma_f32_16x16x32_bf16 v[114:117], v[164:167], v[172:175], v[114:117]
	v_mfma_f32_16x16x32_bf16 v[102:105], v[146:149], v[186:189], v[102:105]
	v_mfma_f32_16x16x32_bf16 v[98:101], v[164:167], v[186:189], v[98:101]
	v_mfma_f32_16x16x32_bf16 v[86:89], v[146:149], v[204:207], v[86:89]
	v_mfma_f32_16x16x32_bf16 v[82:85], v[164:167], v[204:207], v[82:85]
	v_mfma_f32_16x16x32_bf16 v[70:73], v[146:149], v[212:215], v[70:73]
	v_mfma_f32_16x16x32_bf16 v[66:69], v[164:167], v[212:215], v[66:69]
	v_mfma_f32_16x16x32_bf16 v[118:121], v[150:153], v[176:179], v[118:121]
	v_mfma_f32_16x16x32_bf16 v[114:117], v[168:171], v[176:179], v[114:117]
	v_mfma_f32_16x16x32_bf16 v[102:105], v[150:153], v[190:193], v[102:105]
	v_mfma_f32_16x16x32_bf16 v[98:101], v[168:171], v[190:193], v[98:101]
	v_mfma_f32_16x16x32_bf16 v[86:89], v[150:153], v[208:211], v[86:89]
	v_mfma_f32_16x16x32_bf16 v[82:85], v[168:171], v[208:211], v[82:85]
	v_mfma_f32_16x16x32_bf16 v[70:73], v[150:153], v[216:219], v[70:73]
	v_mfma_f32_16x16x32_bf16 v[66:69], v[168:171], v[216:219], v[66:69]
	s_setprio 0
	s_barrier
	s_mov_b32 m0, s56
	v_lshl_add_u64 v[180:181], v[180:181], 0, s[80:81]
	s_add_u32 s28, s28, 0x100080
	ds_read_b128 v[172:175], v185 offset:49152
	ds_read_b128 v[176:179], v185 offset:50176
	ds_read_b128 v[186:189], v185 offset:51200
	ds_read_b128 v[190:193], v185 offset:52224
	ds_read_b128 v[204:207], v185 offset:53248
	ds_read_b128 v[208:211], v185 offset:54272
	ds_read_b128 v[212:215], v185 offset:55296
	ds_read_b128 v[216:219], v185 offset:56320
	global_load_lds_dwordx4 v[180:181], off
	v_lshl_add_u64 v[180:181], v[200:201], 0, s[80:81]
	s_mov_b32 m0, s57
	s_addc_u32 s29, s29, 0
	global_load_lds_dwordx4 v[180:181], off
	v_lshl_add_u64 v[180:181], s[28:29], 0, v[0:1]
	s_mov_b32 m0, s61
	s_nop 0
	global_load_lds_dwordx4 v[180:181], off
	v_lshl_add_u64 v[180:181], s[28:29], 0, v[158:159]
	s_mov_b32 m0, s62
	s_nop 0
	global_load_lds_dwordx4 v[180:181], off
	v_lshl_add_u64 v[180:181], v[220:221], 0, s[80:81]
	s_mov_b32 m0, s58
	s_nop 0
	global_load_lds_dwordx4 v[180:181], off
	v_lshl_add_u64 v[180:181], v[222:223], 0, s[80:81]
	s_mov_b32 m0, s59
	s_nop 0
	global_load_lds_dwordx4 v[180:181], off
	s_waitcnt vmcnt(8)
	s_waitcnt lgkmcnt(0)
	s_barrier
	s_setprio 1
	s_waitcnt lgkmcnt(0)
	v_mfma_f32_16x16x32_bf16 v[62:65], v[130:133], v[172:175], v[62:65]
	v_mfma_f32_16x16x32_bf16 v[58:61], v[138:141], v[172:175], v[58:61]
	v_mfma_f32_16x16x32_bf16 v[46:49], v[130:133], v[186:189], v[46:49]
	v_mfma_f32_16x16x32_bf16 v[42:45], v[138:141], v[186:189], v[42:45]
	v_mfma_f32_16x16x32_bf16 v[30:33], v[130:133], v[204:207], v[30:33]
	v_mfma_f32_16x16x32_bf16 v[26:29], v[138:141], v[204:207], v[26:29]
	v_mfma_f32_16x16x32_bf16 v[14:17], v[130:133], v[212:215], v[14:17]
	v_mfma_f32_16x16x32_bf16 v[10:13], v[138:141], v[212:215], v[10:13]
	v_mfma_f32_16x16x32_bf16 v[62:65], v[134:137], v[176:179], v[62:65]
	v_mfma_f32_16x16x32_bf16 v[58:61], v[142:145], v[176:179], v[58:61]
	v_mfma_f32_16x16x32_bf16 v[46:49], v[134:137], v[190:193], v[46:49]
	v_mfma_f32_16x16x32_bf16 v[42:45], v[142:145], v[190:193], v[42:45]
	v_mfma_f32_16x16x32_bf16 v[30:33], v[134:137], v[208:211], v[30:33]
	v_mfma_f32_16x16x32_bf16 v[26:29], v[142:145], v[208:211], v[26:29]
	v_mfma_f32_16x16x32_bf16 v[14:17], v[134:137], v[216:219], v[14:17]
	v_mfma_f32_16x16x32_bf16 v[10:13], v[142:145], v[216:219], v[10:13]
	v_mfma_f32_16x16x32_bf16 v[54:57], v[146:149], v[172:175], v[54:57]
	v_mfma_f32_16x16x32_bf16 v[50:53], v[164:167], v[172:175], v[50:53]
	v_mfma_f32_16x16x32_bf16 v[38:41], v[146:149], v[186:189], v[38:41]
	v_mfma_f32_16x16x32_bf16 v[34:37], v[164:167], v[186:189], v[34:37]
	v_mfma_f32_16x16x32_bf16 v[22:25], v[146:149], v[204:207], v[22:25]
	v_mfma_f32_16x16x32_bf16 v[18:21], v[164:167], v[204:207], v[18:21]
	v_mfma_f32_16x16x32_bf16 v[6:9], v[146:149], v[212:215], v[6:9]
	v_mfma_f32_16x16x32_bf16 v[2:5], v[164:167], v[212:215], v[2:5]
	v_mfma_f32_16x16x32_bf16 v[54:57], v[150:153], v[176:179], v[54:57]
	v_mfma_f32_16x16x32_bf16 v[50:53], v[168:171], v[176:179], v[50:53]
	v_mfma_f32_16x16x32_bf16 v[38:41], v[150:153], v[190:193], v[38:41]
	v_mfma_f32_16x16x32_bf16 v[34:37], v[168:171], v[190:193], v[34:37]
	v_mfma_f32_16x16x32_bf16 v[22:25], v[150:153], v[208:211], v[22:25]
	v_mfma_f32_16x16x32_bf16 v[18:21], v[168:171], v[208:211], v[18:21]
	v_mfma_f32_16x16x32_bf16 v[6:9], v[150:153], v[216:219], v[6:9]
	v_mfma_f32_16x16x32_bf16 v[2:5], v[168:171], v[216:219], v[2:5]
	s_setprio 0
	s_barrier
	s_add_i32 s68, s68, 2
	s_add_u32 s26, s26, 0x100
	s_addc_u32 s27, s27, 0
	s_add_u32 s66, s66, 0x100
	s_addc_u32 s67, s67, 0
	s_cmp_gt_u32 s68, 61
	s_cbranch_scc0 .LBB0_1325
	s_and_b64 vcc, exec, s[12:13]
	s_cbranch_vccz .LBB0_1328
	s_barrier
